# dilated-window unit compute part hand-scheduled (immediate-offset bias gather, range-compare window mask, fused exp/PV); M1 row statistics preloaded before the K loop; static first attention-queue ite
# speedup vs baseline: 1.0700x; 1.0145x over previous
; DI int ltid() { int t = threadIdx.x; asm volatile("" : "+v"(t)); return t; }
; #define QUEUE_BEGIN(n) for (;;) { __syncthreads(); if (tid == 0) *s_item = atomicAdd(WSP(int, WS_CTR) + ph + 50 * rep_, 1); __syncthreads(); const int item = *s_item; if (item >= (n)) break;
; __global__ void __launch_bounds__(512, 2) mega(Params p) {
;     ...
;             case OP_ATT_MLA: {
;     ...
;                 const int tid = ltid();
;                 QUEUE_BEGIN(512 + 256)
;                     if (item >= 256 && item < 512) {
;                         bf16_t* P = (bf16_t*)(R1 + R_P);
;                         const int qt = 15 - ((item - 256) >> 4), bl = (item >> 3) & 1, h = item & 7;
;                         AttnArgs a; a.Q = P + C_SBQ + h * 64; a.ldq = NINP; a.K = P + C_SBK + h * 64; a.ldk = NINP; a.K2 = nullptr; a.ldk2 = 0;
;                         a.V = P + C_SBV + h * 64; a.ldv = NINP; a.O = (bf16_t*)(R1 + R_OA) + h * 64; a.ldo = 512; a.lse = nullptr; a.ldl = 0;
;                         a.q0 = qt * 256; a.tstride = 1; a.toff = bl * SEQ; a.nk = 0; a.c2 = 0.125f * LOG2E; a.biasg = nullptr;
;                         attn_unit<2>(lds, a);
;                     } else if (item < 256) {
;                         const int qt = 15 - (item >> 4), bl = (item >> 3) & 1, h = item & 7;
;                         bf16_t* kvm = (bf16_t*)(R1 + R_KVM);
;                         AttnArgs a; a.Q = (bf16_t*)(R1 + R_QM) + h * 96; a.ldq = 768; a.K = kvm + h * 128; a.ldk = 1024; a.K2 = (bf16_t*)(R1 + R_P) + C_KR; a.ldk2 = NINP;
;                         a.V = kvm + h * 128 + 64; a.ldv = 1024; a.O = (bf16_t*)(R1 + R_OA) + (size_t)TC * 512 + h * 64; a.ldo = 512; a.lse = nullptr; a.ldl = 0;
;                         a.q0 = qt * 256; a.tstride = 1; a.toff = bl * SEQ; a.nk = 0; a.c2 = 0.10206207261596577f * LOG2E; a.biasg = nullptr;
;                         attn_unit<1>(lds, a);
;                     } else {
;                         const int t0 = (item - 512) * 32;
;                         bf16_t* oc = (bf16_t*)(R1 + R_OA) + (size_t)2 * TC * 512;
;                         const bf16_t* og = (const bf16_t*)(R1 + R_OG);
;                         const float* lse = (const float*)(R1 + R_LSE);
.LBB0_109:
	s_andn2_b64 vcc, exec, s[6:7]
	s_cbranch_vccnz .LBB0_223
	s_load_dwordx2 s[4:5], s[70:71], 0xe8
	v_readlane_b32 s0, v254, 6
	v_readlane_b32 s1, v254, 7
	s_lshl_b64 s[0:1], s[0:1], 2
	v_mov_b32_e32 v2, v202
	s_waitcnt lgkmcnt(0)
	s_add_u32 s0, s4, s0
	s_addc_u32 s1, s5, s1
	v_writelane_b32 v255, s0, 11
	s_nop 0
	v_lshrrev_b32_e32 v0, 1, v2
	v_writelane_b32 v255, s1, 12
	s_add_u32 s0, s4, 0xcb4a200
	s_addc_u32 s1, s5, 0
	v_writelane_b32 v255, s0, 13
	v_and_b32_e32 v0, 28, v0
	v_cmp_eq_u32_e64 s[12:13], 0, v2
	v_writelane_b32 v255, s1, 14
	s_add_u32 s0, s4, 0x1a349200
	v_writelane_b32 v255, s0, 15
	s_addc_u32 s0, s5, 0
	v_writelane_b32 v255, s0, 16
	s_add_u32 s0, s4, 0xcb49600
	v_writelane_b32 v255, s0, 17
	s_addc_u32 s0, s5, 0
	v_writelane_b32 v255, s0, 18
	s_add_u32 s0, s4, 0xcb49a00
	s_addc_u32 s1, s5, 0
	v_writelane_b32 v255, s0, 19
	v_ashrrev_i32_e32 v196, 6, v2
	v_add_u32_e32 v197, 0xffffc000, v196
	v_writelane_b32 v255, s1, 20
	s_nop 0
	v_readlane_b32 s0, v255, 9
	v_readlane_b32 s1, v255, 10
	s_nop 1
	v_lshl_add_u64 v[136:137], s[0:1], 0, v[0:1]
	v_readlane_b32 s0, v255, 7
	v_lshlrev_b32_e32 v0, 4, v2
	v_readlane_b32 s1, v255, 8
	v_writelane_b32 v255, s12, 21
	v_and_b32_e32 v0, 0x3f0, v0
	v_lshl_add_u64 v[138:139], s[0:1], 0, v[0:1]
	v_writelane_b32 v255, s13, 22
	v_lshl_add_u64 v[2:3], s[4:5], 0, v[0:1]
	s_mov_b64 s[0:1], 0x1ab49200
	v_writelane_b32 v255, s70, 23
	v_lshl_add_u64 v[140:141], v[2:3], 0, s[0:1]
	s_nop 0
	v_writelane_b32 v255, s71, 24
	s_mov_b32 s99, 1
	s_branch .LBB0_114

.LBB0_114:
	s_cmp_eq_u32 s99, 0
	s_cbranch_scc1 .Lq_dyn
	s_mov_b32 s99, 0
	s_add_i32 s18, s76, 0xe0
	s_and_b32 s18, s18, 0xff
	s_mov_b64 s[6:7], -1
	s_branch .Lq_have

; DI unsigned pk2(float lo, float hi) { f32x2_t v = {lo, hi}; bf16x2_t b = __builtin_convertvector(v, bf16x2_t); return __builtin_bit_cast(unsigned, b); }
; DI float bflo(unsigned u) { return __uint_as_float(u << 16); }
; DI float bfhi(unsigned u) { return __uint_as_float(u & 0xffff0000u); }
; DI float ex2(float x) { return __builtin_amdgcn_exp2f(x); }
; __global__ void __launch_bounds__(512, 2) mega(Params p) {
;     ...
;                         const int t0 = (item - 512) * 32;
;                         bf16_t* oc = (bf16_t*)(R1 + R_OA) + (size_t)2 * TC * 512;
;                         const bf16_t* og = (const bf16_t*)(R1 + R_OG);
;                         const float* lse = (const float*)(R1 + R_LSE);
; #pragma unroll
;                         for (int ps = 0; ps < 4; ++ps) {
;                             const int tok = t0 + ps * 8 + (tid >> 6), c8 = (tid & 63) * 8, h = c8 >> 6;
;                             const float l0 = lse[(size_t)tok * 8 + h], l1 = lse[(size_t)(TC + tok) * 8 + h], l2 = lse[(size_t)(2 * TC + tok) * 8 + h];
;                             const float mx = fmaxf(l0, fmaxf(l1, l2));
;                             float w0 = ex2(l0 - mx), w1 = ex2(l1 - mx), w2 = ex2(l2 - mx);
;                             const float is = 1.0f / (w0 + w1 + w2); w0 *= is; w1 *= is; w2 *= is;
;                             const u32x4 a0 = *(const u32x4*)(og + (size_t)tok * 512 + c8), a1 = *(const u32x4*)(og + (size_t)(TC + tok) * 512 + c8), a2 = *(const u32x4*)(og + (size_t)(2 * TC + tok) * 512 + c8);
;                             u32x4 w;
;                             w.x = pk2(w0 * bflo(a0.x) + w1 * bflo(a1.x) + w2 * bflo(a2.x), w0 * bfhi(a0.x) + w1 * bfhi(a1.x) + w2 * bfhi(a2.x));
;                             w.y = pk2(w0 * bflo(a0.y) + w1 * bflo(a1.y) + w2 * bflo(a2.y), w0 * bfhi(a0.y) + w1 * bfhi(a1.y) + w2 * bfhi(a2.y));
;                             w.z = pk2(w0 * bflo(a0.z) + w1 * bflo(a1.z) + w2 * bflo(a2.z), w0 * bfhi(a0.z) + w1 * bfhi(a1.z) + w2 * bfhi(a2.z));
;                             w.w = pk2(w0 * bflo(a0.w) + w1 * bflo(a1.w) + w2 * bflo(a2.w), w0 * bfhi(a0.w) + w1 * bfhi(a1.w) + w2 * bfhi(a2.w));
;                             *(u32x4*)(oc + (size_t)tok * 512 + c8) = w;
;                         }
.LBB0_118:
	s_or_b64 exec, exec, s[6:7]
	s_mov_b32 s0, 0x20000
	s_addk_i32 s0, 0x100
	v_mov_b32_e32 v0, s0
	s_waitcnt lgkmcnt(0)
	s_barrier
	ds_read_b32 v0, v0
	s_movk_i32 s0, 0x21f
	s_mov_b64 s[6:7], -1
	s_waitcnt lgkmcnt(0)
	v_cmp_lt_i32_e32 vcc, s0, v0
	v_readfirstlane_b32 s18, v0
	s_cbranch_vccnz .LBB0_113
	s_addk_i32 s18, 0x100
.Lq_have:
	s_cmpk_lt_i32 s18, 0x120
	s_cbranch_scc1 .LBB0_122
	s_addk_i32 s18, 0xffe0
	s_and_b32 s0, s18, 0xffffff00
	s_cmpk_lg_i32 s0, 0x100
	s_cbranch_scc0 .LBB0_188
	s_cmpk_gt_i32 s18, 0xff
	s_cbranch_scc0 .LBB0_122
	s_lshl_b32 s0, s18, 5
	v_add_u32_e32 v2, s0, v197
	v_ashrrev_i32_e32 v3, 31, v2
	v_lshlrev_b64 v[4:5], 5, v[2:3]
	v_add_u32_e32 v8, 0x2000, v2
	v_lshl_add_u64 v[4:5], v[136:137], 0, v[4:5]
	v_ashrrev_i32_e32 v9, 31, v8
	global_load_dword v0, v[4:5], off
	v_lshlrev_b64 v[4:5], 5, v[8:9]
	v_add_u32_e32 v12, s0, v196
	v_lshl_add_u64 v[4:5], v[136:137], 0, v[4:5]
	v_ashrrev_i32_e32 v13, 31, v12
	global_load_dword v6, v[4:5], off
	v_lshlrev_b64 v[4:5], 5, v[12:13]
	v_lshl_add_u64 v[4:5], v[136:137], 0, v[4:5]
	global_load_dword v4, v[4:5], off
	v_lshlrev_b64 v[12:13], 10, v[12:13]
	v_lshl_add_u64 v[12:13], v[138:139], 0, v[12:13]
	global_load_dwordx4 v[12:15], v[12:13], off
	v_lshlrev_b64 v[20:21], 10, v[2:3]
	v_lshlrev_b64 v[8:9], 10, v[8:9]
	v_lshl_add_u64 v[8:9], v[138:139], 0, v[8:9]
	s_mov_b64 s[6:7], 0
	s_waitcnt vmcnt(0)
	v_max3_f32 v5, v0, v6, v4
	v_sub_f32_e32 v0, v0, v5
	v_exp_f32_e32 v17, v0
	v_sub_f32_e32 v0, v6, v5
	v_exp_f32_e32 v16, v0
	v_sub_f32_e32 v0, v4, v5
	v_exp_f32_e32 v4, v0
	s_waitcnt vmcnt(0)
	v_lshlrev_b32_e32 v26, 16, v12
	v_add_f32_e32 v0, v17, v16
	v_and_b32_e32 v27, 0xffff0000, v12
	v_add_f32_e32 v0, v4, v0
	v_div_scale_f32 v5, s[0:1], v0, v0, 1.0
	v_rcp_f32_e32 v6, v5
	v_lshlrev_b32_e32 v12, 16, v13
	v_and_b32_e32 v13, 0xffff0000, v13
	v_fma_f32 v7, -v5, v6, 1.0
	v_fmac_f32_e32 v6, v7, v6
	v_div_scale_f32 v7, vcc, 1.0, v0, 1.0
	v_mul_f32_e32 v10, v7, v6
	v_fma_f32 v11, -v5, v10, v7
	v_fmac_f32_e32 v10, v11, v6
	v_fma_f32 v5, -v5, v10, v7
	v_div_fmas_f32 v5, v5, v6, v10
	v_div_fixup_f32 v0, v5, v0, 1.0
	v_mul_f32_e32 v18, v4, v0
	v_lshl_add_u64 v[4:5], v[138:139], 0, v[20:21]
	global_load_dwordx4 v[4:7], v[4:5], off
	v_pk_mul_f32 v[16:17], v[16:17], v[0:1] op_sel_hi:[1,0]
	global_load_dwordx4 v[8:11], v[8:9], off
	s_waitcnt vmcnt(1)
	v_lshlrev_b32_e32 v24, 16, v4
	v_and_b32_e32 v23, 0xffff0000, v4
	s_waitcnt vmcnt(0)
	v_and_b32_e32 v25, 0xffff0000, v8
	v_lshlrev_b32_e32 v22, 16, v8
	v_pk_mul_f32 v[24:25], v[16:17], v[24:25] op_sel:[1,0] op_sel_hi:[0,1]
	v_pk_fma_f32 v[22:23], v[16:17], v[22:23], v[24:25]
	v_lshlrev_b32_e32 v8, 16, v5
	v_pk_fma_f32 v[22:23], v[18:19], v[26:27], v[22:23] op_sel_hi:[0,1,1]
	v_cvt_pk_bf16_f32 v4, v22, v23
	v_lshlrev_b32_e32 v22, 16, v9
	v_and_b32_e32 v9, 0xffff0000, v9
	v_and_b32_e32 v23, 0xffff0000, v5
	v_pk_mul_f32 v[8:9], v[16:17], v[8:9] op_sel:[1,0] op_sel_hi:[0,1]
	v_pk_fma_f32 v[8:9], v[16:17], v[22:23], v[8:9]
	v_lshlrev_b32_e32 v22, 16, v14
	v_pk_fma_f32 v[8:9], v[18:19], v[12:13], v[8:9] op_sel_hi:[0,1,1]
	v_lshlrev_b32_e32 v12, 16, v6
	v_and_b32_e32 v13, 0xffff0000, v10
	v_cvt_pk_bf16_f32 v5, v8, v9
	v_lshlrev_b32_e32 v8, 16, v10
	v_and_b32_e32 v9, 0xffff0000, v6
	v_pk_mul_f32 v[12:13], v[16:17], v[12:13] op_sel:[1,0] op_sel_hi:[0,1]
	v_and_b32_e32 v23, 0xffff0000, v14
	v_pk_fma_f32 v[8:9], v[16:17], v[8:9], v[12:13]
	v_lshlrev_b32_e32 v10, 16, v7
	v_pk_fma_f32 v[8:9], v[18:19], v[22:23], v[8:9] op_sel_hi:[0,1,1]
	v_cvt_pk_bf16_f32 v6, v8, v9
	v_lshlrev_b32_e32 v8, 16, v11
	v_and_b32_e32 v11, 0xffff0000, v11
	v_and_b32_e32 v9, 0xffff0000, v7
	v_pk_mul_f32 v[10:11], v[16:17], v[10:11] op_sel:[1,0] op_sel_hi:[0,1]
	v_pk_fma_f32 v[8:9], v[16:17], v[8:9], v[10:11]
	v_lshlrev_b32_e32 v10, 16, v15
	v_and_b32_e32 v11, 0xffff0000, v15
	v_pk_fma_f32 v[8:9], v[18:19], v[10:11], v[8:9] op_sel_hi:[0,1,1]
	v_cvt_pk_bf16_f32 v7, v8, v9
	v_lshl_add_u64 v[8:9], v[140:141], 0, v[20:21]
	global_store_dwordx4 v[8:9], v[4:7], off
	v_add_u32_e32 v8, 0x2008, v2
	v_ashrrev_i32_e32 v9, 31, v8
	v_add_u32_e32 v4, 8, v2
	v_ashrrev_i32_e32 v5, 31, v4
	v_lshlrev_b64 v[6:7], 5, v[4:5]
	v_lshl_add_u64 v[6:7], v[136:137], 0, v[6:7]
	global_load_dword v0, v[6:7], off
	v_lshlrev_b64 v[6:7], 5, v[8:9]
	v_add_u32_e32 v12, 0x4008, v2
	v_lshl_add_u64 v[6:7], v[136:137], 0, v[6:7]
	v_ashrrev_i32_e32 v13, 31, v12
	global_load_dword v3, v[6:7], off
	v_lshlrev_b64 v[6:7], 5, v[12:13]
	v_lshl_add_u64 v[6:7], v[136:137], 0, v[6:7]
	global_load_dword v6, v[6:7], off
	v_lshlrev_b64 v[20:21], 10, v[4:5]
	v_lshlrev_b64 v[8:9], 10, v[8:9]
	v_lshl_add_u64 v[4:5], v[138:139], 0, v[20:21]
	v_lshl_add_u64 v[8:9], v[138:139], 0, v[8:9]
	v_lshlrev_b64 v[12:13], 10, v[12:13]
	v_lshl_add_u64 v[12:13], v[138:139], 0, v[12:13]
	s_waitcnt vmcnt(0)
	v_max3_f32 v7, v0, v3, v6
	v_sub_f32_e32 v0, v0, v7
	v_exp_f32_e32 v17, v0
	v_sub_f32_e32 v0, v3, v7
	v_exp_f32_e32 v16, v0
	v_sub_f32_e32 v0, v6, v7
	v_exp_f32_e32 v3, v0
	v_add_f32_e32 v0, v17, v16
	v_add_f32_e32 v0, v3, v0
	v_div_scale_f32 v6, s[0:1], v0, v0, 1.0
	v_rcp_f32_e32 v7, v6
	s_nop 0
	v_fma_f32 v10, -v6, v7, 1.0
	v_fmac_f32_e32 v7, v10, v7
	v_div_scale_f32 v10, vcc, 1.0, v0, 1.0
	v_mul_f32_e32 v11, v10, v7
	v_fma_f32 v14, -v6, v11, v10
	v_fmac_f32_e32 v11, v14, v7
	v_fma_f32 v6, -v6, v11, v10
	v_div_fmas_f32 v6, v6, v7, v11
	v_div_fixup_f32 v0, v6, v0, 1.0
	global_load_dwordx4 v[4:7], v[4:5], off
	v_pk_mul_f32 v[16:17], v[16:17], v[0:1] op_sel_hi:[1,0]
	global_load_dwordx4 v[8:11], v[8:9], off
	v_mul_f32_e32 v18, v3, v0
	global_load_dwordx4 v[12:15], v[12:13], off
	s_waitcnt vmcnt(2)
	v_lshlrev_b32_e32 v24, 16, v4
	v_and_b32_e32 v23, 0xffff0000, v4
	s_waitcnt vmcnt(1)
; DI unsigned pk2(float lo, float hi) { f32x2_t v = {lo, hi}; bf16x2_t b = __builtin_convertvector(v, bf16x2_t); return __builtin_bit_cast(unsigned, b); }
; DI float bflo(unsigned u) { return __uint_as_float(u << 16); }
; DI float bfhi(unsigned u) { return __uint_as_float(u & 0xffff0000u); }
; DI float ex2(float x) { return __builtin_amdgcn_exp2f(x); }
; __global__ void __launch_bounds__(512, 2) mega(Params p) {
;     ...
;                         for (int ps = 0; ps < 4; ++ps) {
;                             const int tok = t0 + ps * 8 + (tid >> 6), c8 = (tid & 63) * 8, h = c8 >> 6;
;                             const float l0 = lse[(size_t)tok * 8 + h], l1 = lse[(size_t)(TC + tok) * 8 + h], l2 = lse[(size_t)(2 * TC + tok) * 8 + h];
;                             const float mx = fmaxf(l0, fmaxf(l1, l2));
;                             float w0 = ex2(l0 - mx), w1 = ex2(l1 - mx), w2 = ex2(l2 - mx);
;                             const float is = 1.0f / (w0 + w1 + w2); w0 *= is; w1 *= is; w2 *= is;
;                             const u32x4 a0 = *(const u32x4*)(og + (size_t)tok * 512 + c8), a1 = *(const u32x4*)(og + (size_t)(TC + tok) * 512 + c8), a2 = *(const u32x4*)(og + (size_t)(2 * TC + tok) * 512 + c8);
;                             u32x4 w;
;                             w.x = pk2(w0 * bflo(a0.x) + w1 * bflo(a1.x) + w2 * bflo(a2.x), w0 * bfhi(a0.x) + w1 * bfhi(a1.x) + w2 * bfhi(a2.x));
;                             w.y = pk2(w0 * bflo(a0.y) + w1 * bflo(a1.y) + w2 * bflo(a2.y), w0 * bfhi(a0.y) + w1 * bfhi(a1.y) + w2 * bfhi(a2.y));
;                             w.z = pk2(w0 * bflo(a0.z) + w1 * bflo(a1.z) + w2 * bflo(a2.z), w0 * bfhi(a0.z) + w1 * bfhi(a1.z) + w2 * bfhi(a2.z));
;                             w.w = pk2(w0 * bflo(a0.w) + w1 * bflo(a1.w) + w2 * bflo(a2.w), w0 * bfhi(a0.w) + w1 * bfhi(a1.w) + w2 * bfhi(a2.w));
;                             *(u32x4*)(oc + (size_t)tok * 512 + c8) = w;
;                         }
	v_and_b32_e32 v25, 0xffff0000, v8
	v_lshlrev_b32_e32 v22, 16, v8
	v_pk_mul_f32 v[24:25], v[16:17], v[24:25] op_sel:[1,0] op_sel_hi:[0,1]
	s_waitcnt vmcnt(0)
	v_lshlrev_b32_e32 v26, 16, v12
	v_and_b32_e32 v27, 0xffff0000, v12
	v_pk_fma_f32 v[22:23], v[16:17], v[22:23], v[24:25]
	v_lshlrev_b32_e32 v8, 16, v5
	v_pk_fma_f32 v[22:23], v[18:19], v[26:27], v[22:23] op_sel_hi:[0,1,1]
	v_cvt_pk_bf16_f32 v4, v22, v23
	v_lshlrev_b32_e32 v22, 16, v9
	v_and_b32_e32 v9, 0xffff0000, v9
	v_and_b32_e32 v23, 0xffff0000, v5
	v_pk_mul_f32 v[8:9], v[16:17], v[8:9] op_sel:[1,0] op_sel_hi:[0,1]
	v_lshlrev_b32_e32 v12, 16, v13
	v_and_b32_e32 v13, 0xffff0000, v13
	v_pk_fma_f32 v[8:9], v[16:17], v[22:23], v[8:9]
	v_lshlrev_b32_e32 v22, 16, v14
	v_pk_fma_f32 v[8:9], v[18:19], v[12:13], v[8:9] op_sel_hi:[0,1,1]
	v_lshlrev_b32_e32 v12, 16, v6
	v_and_b32_e32 v13, 0xffff0000, v10
	v_cvt_pk_bf16_f32 v5, v8, v9
	v_lshlrev_b32_e32 v8, 16, v10
	v_and_b32_e32 v9, 0xffff0000, v6
	v_pk_mul_f32 v[12:13], v[16:17], v[12:13] op_sel:[1,0] op_sel_hi:[0,1]
	v_and_b32_e32 v23, 0xffff0000, v14
	v_pk_fma_f32 v[8:9], v[16:17], v[8:9], v[12:13]
	v_lshlrev_b32_e32 v10, 16, v7
	v_pk_fma_f32 v[8:9], v[18:19], v[22:23], v[8:9] op_sel_hi:[0,1,1]
	v_cvt_pk_bf16_f32 v6, v8, v9
	v_lshlrev_b32_e32 v8, 16, v11
	v_and_b32_e32 v11, 0xffff0000, v11
	v_and_b32_e32 v9, 0xffff0000, v7
	v_pk_mul_f32 v[10:11], v[16:17], v[10:11] op_sel:[1,0] op_sel_hi:[0,1]
	v_pk_fma_f32 v[8:9], v[16:17], v[8:9], v[10:11]
	v_lshlrev_b32_e32 v10, 16, v15
	v_and_b32_e32 v11, 0xffff0000, v15
	v_pk_fma_f32 v[8:9], v[18:19], v[10:11], v[8:9] op_sel_hi:[0,1,1]
	v_cvt_pk_bf16_f32 v7, v8, v9
	v_lshl_add_u64 v[8:9], v[140:141], 0, v[20:21]
	global_store_dwordx4 v[8:9], v[4:7], off
	v_add_u32_e32 v8, 0x2010, v2
	v_ashrrev_i32_e32 v9, 31, v8
	v_add_u32_e32 v4, 16, v2
	v_ashrrev_i32_e32 v5, 31, v4
	v_lshlrev_b64 v[6:7], 5, v[4:5]
	v_lshl_add_u64 v[6:7], v[136:137], 0, v[6:7]
	global_load_dword v0, v[6:7], off
	v_lshlrev_b64 v[6:7], 5, v[8:9]
	v_add_u32_e32 v12, 0x4010, v2
	v_lshl_add_u64 v[6:7], v[136:137], 0, v[6:7]
	v_ashrrev_i32_e32 v13, 31, v12
	global_load_dword v3, v[6:7], off
	v_lshlrev_b64 v[6:7], 5, v[12:13]
	v_lshl_add_u64 v[6:7], v[136:137], 0, v[6:7]
	global_load_dword v6, v[6:7], off
	v_lshlrev_b64 v[20:21], 10, v[4:5]
	v_lshlrev_b64 v[8:9], 10, v[8:9]
	v_lshl_add_u64 v[4:5], v[138:139], 0, v[20:21]
	v_lshl_add_u64 v[8:9], v[138:139], 0, v[8:9]
	v_lshlrev_b64 v[12:13], 10, v[12:13]
	v_lshl_add_u64 v[12:13], v[138:139], 0, v[12:13]
	s_waitcnt vmcnt(0)
	v_max3_f32 v7, v0, v3, v6
	v_sub_f32_e32 v0, v0, v7
	v_exp_f32_e32 v17, v0
	v_sub_f32_e32 v0, v3, v7
	v_exp_f32_e32 v16, v0
	v_sub_f32_e32 v0, v6, v7
	v_exp_f32_e32 v3, v0
	v_add_f32_e32 v0, v17, v16
	v_add_f32_e32 v0, v3, v0
	v_div_scale_f32 v6, s[0:1], v0, v0, 1.0
	v_rcp_f32_e32 v7, v6
	s_nop 0
	v_fma_f32 v10, -v6, v7, 1.0
	v_fmac_f32_e32 v7, v10, v7
	v_div_scale_f32 v10, vcc, 1.0, v0, 1.0
	v_mul_f32_e32 v11, v10, v7
	v_fma_f32 v14, -v6, v11, v10
	v_fmac_f32_e32 v11, v14, v7
	v_fma_f32 v6, -v6, v11, v10
	v_div_fmas_f32 v6, v6, v7, v11
	v_div_fixup_f32 v0, v6, v0, 1.0
	global_load_dwordx4 v[4:7], v[4:5], off
	v_pk_mul_f32 v[16:17], v[16:17], v[0:1] op_sel_hi:[1,0]
	global_load_dwordx4 v[8:11], v[8:9], off
	v_mul_f32_e32 v18, v3, v0
	global_load_dwordx4 v[12:15], v[12:13], off
	s_waitcnt vmcnt(2)
	v_lshlrev_b32_e32 v24, 16, v4
	v_and_b32_e32 v23, 0xffff0000, v4
	s_waitcnt vmcnt(1)
	v_and_b32_e32 v25, 0xffff0000, v8
	v_lshlrev_b32_e32 v22, 16, v8
	v_pk_mul_f32 v[24:25], v[16:17], v[24:25] op_sel:[1,0] op_sel_hi:[0,1]
	s_waitcnt vmcnt(0)
; DI unsigned pk2(float lo, float hi) { f32x2_t v = {lo, hi}; bf16x2_t b = __builtin_convertvector(v, bf16x2_t); return __builtin_bit_cast(unsigned, b); }
; DI float bflo(unsigned u) { return __uint_as_float(u << 16); }
; DI float bfhi(unsigned u) { return __uint_as_float(u & 0xffff0000u); }
; DI float ex2(float x) { return __builtin_amdgcn_exp2f(x); }
; __global__ void __launch_bounds__(512, 2) mega(Params p) {
;     ...
;                         for (int ps = 0; ps < 4; ++ps) {
;                             const int tok = t0 + ps * 8 + (tid >> 6), c8 = (tid & 63) * 8, h = c8 >> 6;
;                             const float l0 = lse[(size_t)tok * 8 + h], l1 = lse[(size_t)(TC + tok) * 8 + h], l2 = lse[(size_t)(2 * TC + tok) * 8 + h];
;                             const float mx = fmaxf(l0, fmaxf(l1, l2));
;                             float w0 = ex2(l0 - mx), w1 = ex2(l1 - mx), w2 = ex2(l2 - mx);
;                             const float is = 1.0f / (w0 + w1 + w2); w0 *= is; w1 *= is; w2 *= is;
;                             const u32x4 a0 = *(const u32x4*)(og + (size_t)tok * 512 + c8), a1 = *(const u32x4*)(og + (size_t)(TC + tok) * 512 + c8), a2 = *(const u32x4*)(og + (size_t)(2 * TC + tok) * 512 + c8);
;                             u32x4 w;
;                             w.x = pk2(w0 * bflo(a0.x) + w1 * bflo(a1.x) + w2 * bflo(a2.x), w0 * bfhi(a0.x) + w1 * bfhi(a1.x) + w2 * bfhi(a2.x));
;                             w.y = pk2(w0 * bflo(a0.y) + w1 * bflo(a1.y) + w2 * bflo(a2.y), w0 * bfhi(a0.y) + w1 * bfhi(a1.y) + w2 * bfhi(a2.y));
;                             w.z = pk2(w0 * bflo(a0.z) + w1 * bflo(a1.z) + w2 * bflo(a2.z), w0 * bfhi(a0.z) + w1 * bfhi(a1.z) + w2 * bfhi(a2.z));
;                             w.w = pk2(w0 * bflo(a0.w) + w1 * bflo(a1.w) + w2 * bflo(a2.w), w0 * bfhi(a0.w) + w1 * bfhi(a1.w) + w2 * bfhi(a2.w));
;                             *(u32x4*)(oc + (size_t)tok * 512 + c8) = w;
;                         }
	v_lshlrev_b32_e32 v26, 16, v12
	v_and_b32_e32 v27, 0xffff0000, v12
	v_pk_fma_f32 v[22:23], v[16:17], v[22:23], v[24:25]
	v_lshlrev_b32_e32 v8, 16, v5
	v_pk_fma_f32 v[22:23], v[18:19], v[26:27], v[22:23] op_sel_hi:[0,1,1]
	v_cvt_pk_bf16_f32 v4, v22, v23
	v_lshlrev_b32_e32 v22, 16, v9
	v_and_b32_e32 v9, 0xffff0000, v9
	v_and_b32_e32 v23, 0xffff0000, v5
	v_pk_mul_f32 v[8:9], v[16:17], v[8:9] op_sel:[1,0] op_sel_hi:[0,1]
	v_lshlrev_b32_e32 v12, 16, v13
	v_and_b32_e32 v13, 0xffff0000, v13
	v_pk_fma_f32 v[8:9], v[16:17], v[22:23], v[8:9]
	v_lshlrev_b32_e32 v22, 16, v14
	v_pk_fma_f32 v[8:9], v[18:19], v[12:13], v[8:9] op_sel_hi:[0,1,1]
	v_lshlrev_b32_e32 v12, 16, v6
	v_and_b32_e32 v13, 0xffff0000, v10
	v_cvt_pk_bf16_f32 v5, v8, v9
	v_lshlrev_b32_e32 v8, 16, v10
	v_and_b32_e32 v9, 0xffff0000, v6
	v_pk_mul_f32 v[12:13], v[16:17], v[12:13] op_sel:[1,0] op_sel_hi:[0,1]
	v_and_b32_e32 v23, 0xffff0000, v14
	v_pk_fma_f32 v[8:9], v[16:17], v[8:9], v[12:13]
	v_lshlrev_b32_e32 v10, 16, v7
	v_pk_fma_f32 v[8:9], v[18:19], v[22:23], v[8:9] op_sel_hi:[0,1,1]
	v_cvt_pk_bf16_f32 v6, v8, v9
	v_lshlrev_b32_e32 v8, 16, v11
	v_and_b32_e32 v11, 0xffff0000, v11
	v_and_b32_e32 v9, 0xffff0000, v7
	v_pk_mul_f32 v[10:11], v[16:17], v[10:11] op_sel:[1,0] op_sel_hi:[0,1]
	v_pk_fma_f32 v[8:9], v[16:17], v[8:9], v[10:11]
	v_lshlrev_b32_e32 v10, 16, v15
	v_and_b32_e32 v11, 0xffff0000, v15
	v_pk_fma_f32 v[8:9], v[18:19], v[10:11], v[8:9] op_sel_hi:[0,1,1]
	v_cvt_pk_bf16_f32 v7, v8, v9
	v_lshl_add_u64 v[8:9], v[140:141], 0, v[20:21]
	global_store_dwordx4 v[8:9], v[4:7], off
	v_add_u32_e32 v12, 0x4018, v2
	v_ashrrev_i32_e32 v13, 31, v12
	v_add_u32_e32 v4, 24, v2
	v_ashrrev_i32_e32 v5, 31, v4
	v_lshlrev_b64 v[6:7], 5, v[4:5]
	v_add_u32_e32 v8, 0x2018, v2
	v_lshlrev_b64 v[2:3], 5, v[12:13]
	v_lshlrev_b64 v[12:13], 10, v[12:13]
	v_lshl_add_u64 v[6:7], v[136:137], 0, v[6:7]
	v_ashrrev_i32_e32 v9, 31, v8
	v_lshl_add_u64 v[2:3], v[136:137], 0, v[2:3]
	v_lshl_add_u64 v[12:13], v[138:139], 0, v[12:13]
	global_load_dword v0, v[6:7], off
	s_nop 0
	global_load_dwordx4 v[12:15], v[12:13], off
	s_waitcnt vmcnt(0)
	v_lshlrev_b32_e32 v24, 16, v12
	global_load_dword v2, v[2:3], off
	v_lshlrev_b64 v[6:7], 5, v[8:9]
	v_lshl_add_u64 v[6:7], v[136:137], 0, v[6:7]
	global_load_dword v6, v[6:7], off
	v_lshlrev_b64 v[8:9], 10, v[8:9]
	v_lshl_add_u64 v[8:9], v[138:139], 0, v[8:9]
	v_and_b32_e32 v25, 0xffff0000, v12
	v_lshlrev_b32_e32 v12, 16, v13
	v_and_b32_e32 v13, 0xffff0000, v13
	s_waitcnt vmcnt(0)
	v_max3_f32 v3, v0, v6, v2
	v_sub_f32_e32 v0, v0, v3
	v_exp_f32_e32 v17, v0
	v_sub_f32_e32 v0, v6, v3
	v_exp_f32_e32 v16, v0
	v_sub_f32_e32 v0, v2, v3
	v_exp_f32_e32 v2, v0
	v_add_f32_e32 v0, v17, v16
	v_add_f32_e32 v0, v2, v0
	v_div_scale_f32 v3, s[0:1], v0, v0, 1.0
	v_rcp_f32_e32 v6, v3
	s_nop 0
	v_fma_f32 v7, -v3, v6, 1.0
	v_fmac_f32_e32 v6, v7, v6
	v_div_scale_f32 v7, vcc, 1.0, v0, 1.0
	v_mul_f32_e32 v10, v7, v6
	v_fma_f32 v11, -v3, v10, v7
	v_fmac_f32_e32 v10, v11, v6
	v_fma_f32 v3, -v3, v10, v7
	v_div_fmas_f32 v3, v3, v6, v10
	v_div_fixup_f32 v0, v3, v0, 1.0
	v_lshlrev_b64 v[6:7], 10, v[4:5]
	v_mul_f32_e32 v18, v2, v0
	v_lshl_add_u64 v[2:3], v[138:139], 0, v[6:7]
	global_load_dwordx4 v[2:5], v[2:3], off
	v_pk_mul_f32 v[16:17], v[16:17], v[0:1] op_sel_hi:[1,0]
	global_load_dwordx4 v[8:11], v[8:9], off
	v_lshl_add_u64 v[6:7], v[140:141], 0, v[6:7]
	s_waitcnt vmcnt(1)
	v_lshlrev_b32_e32 v22, 16, v2
	v_and_b32_e32 v21, 0xffff0000, v2
	s_waitcnt vmcnt(0)
	v_and_b32_e32 v23, 0xffff0000, v8
	v_lshlrev_b32_e32 v20, 16, v8
	v_pk_mul_f32 v[22:23], v[16:17], v[22:23] op_sel:[1,0] op_sel_hi:[0,1]
	v_pk_fma_f32 v[20:21], v[16:17], v[20:21], v[22:23]
	v_lshlrev_b32_e32 v8, 16, v3
	v_pk_fma_f32 v[20:21], v[18:19], v[24:25], v[20:21] op_sel_hi:[0,1,1]
	v_cvt_pk_bf16_f32 v2, v20, v21
	v_lshlrev_b32_e32 v20, 16, v9
	v_and_b32_e32 v9, 0xffff0000, v9
	v_and_b32_e32 v21, 0xffff0000, v3
	v_pk_mul_f32 v[8:9], v[16:17], v[8:9] op_sel:[1,0] op_sel_hi:[0,1]
	v_pk_fma_f32 v[8:9], v[16:17], v[20:21], v[8:9]
	v_lshlrev_b32_e32 v20, 16, v14
	v_pk_fma_f32 v[8:9], v[18:19], v[12:13], v[8:9] op_sel_hi:[0,1,1]
	v_lshlrev_b32_e32 v12, 16, v4
	v_and_b32_e32 v13, 0xffff0000, v10
	v_cvt_pk_bf16_f32 v3, v8, v9
	v_lshlrev_b32_e32 v8, 16, v10
	v_and_b32_e32 v9, 0xffff0000, v4
	v_pk_mul_f32 v[12:13], v[16:17], v[12:13] op_sel:[1,0] op_sel_hi:[0,1]
	v_and_b32_e32 v21, 0xffff0000, v14
	v_pk_fma_f32 v[8:9], v[16:17], v[8:9], v[12:13]
	v_lshlrev_b32_e32 v10, 16, v5
	v_pk_fma_f32 v[8:9], v[18:19], v[20:21], v[8:9] op_sel_hi:[0,1,1]
	v_cvt_pk_bf16_f32 v4, v8, v9
	v_lshlrev_b32_e32 v8, 16, v11
	v_and_b32_e32 v11, 0xffff0000, v11
	v_and_b32_e32 v9, 0xffff0000, v5
	v_pk_mul_f32 v[10:11], v[16:17], v[10:11] op_sel:[1,0] op_sel_hi:[0,1]
	v_pk_fma_f32 v[8:9], v[16:17], v[8:9], v[10:11]
	v_lshlrev_b32_e32 v10, 16, v15
	v_and_b32_e32 v11, 0xffff0000, v15
	v_pk_fma_f32 v[8:9], v[18:19], v[10:11], v[8:9] op_sel_hi:[0,1,1]
	v_cvt_pk_bf16_f32 v5, v8, v9
	global_store_dwordx4 v[6:7], v[2:5], off

; #define LAS __attribute__((address_space(3)))
; DI int crow(int i, int hh) { return (i & 3) + 8 * (i >> 2) + 4 * hh; }
; #define MFMA32(a, b, c) __builtin_amdgcn_mfma_f32_32x32x16_bf16((a), (b), (c), 0, 0, 0)
; DI void attn_dil_unit(LAS unsigned char* lds, const AttnArgs a) {
;     ...
;         if (tid < 129) biasL[tid] = bv;
; #pragma unroll
;         for (int i = 0; i < 6; ++i) {
;             const int c = tid + 512 * i, row = c >> 3, ch = c & 7;
;             *(LAS u32x4*)(Kl + row * KLD + ch * 8) = kr[i];
;             const u32x4 v = vr[i];
;             LAS bf16_t* dst = Vl + (ch * 8) * VLD + (row ^ (ch << 2));
;             dst[0 * VLD] = (bf16_t)(v.x & 0xffff); dst[1 * VLD] = (bf16_t)(v.x >> 16);
;             dst[2 * VLD] = (bf16_t)(v.y & 0xffff); dst[3 * VLD] = (bf16_t)(v.y >> 16);
;             dst[4 * VLD] = (bf16_t)(v.z & 0xffff); dst[5 * VLD] = (bf16_t)(v.z >> 16);
;             dst[6 * VLD] = (bf16_t)(v.w & 0xffff); dst[7 * VLD] = (bf16_t)(v.w >> 16);
;         }
;     }
;     __syncthreads();
;     f32x16 sc[5];
; #pragma unroll
;     for (int j = 0; j < 5; ++j) {
; #pragma unroll
;         for (int i = 0; i < 16; ++i) sc[j][i] = 0.f;
; #pragma unroll
;         for (int ks = 0; ks < 4; ++ks) {
;             const bf16x8 kf = *(const LAS bf16x8*)(Kl + (32 * wid + 32 * j + r32) * KLD + ks * 16 + 8 * hh);
;             sc[j] = MFMA32(kf, qf[ks], sc[j]);
;         }
;     }
;     float mx = -1e30f;
; #pragma unroll
;     for (int j = 0; j < 5; ++j)
; #pragma unroll
;         for (int i = 0; i < 16; ++i) {
;             const int st = r32 + 128 - 32 * j - crow(i, hh);
;             const int kj = qi - st;
;             const bool valid = (st >= 0) && (st <= 128) && (kj >= 0);
;             float x = sc[j][i] * a.c2 + biasL[min(max(st, 0), 128)];
.LBB0_232:
	s_or_b64 exec, exec, s[6:7]
	v_and_b32_e32 v57, 7, v96
	s_waitcnt vmcnt(0)
	v_lshl_add_u32 v56, v57, 4, v240
	s_movk_i32 s1, 0x1870
	v_mad_u32_u24 v60, v57, s1, v56
	v_lshlrev_b32_e32 v57, 2, v57
	s_movk_i32 s1, 0x90
	v_mad_u64_u32 v[58:59], s[4:5], v50, s1, v[56:57]
	ds_write_b128 v58, v[22:25]
	v_xor_b32_e32 v22, v57, v50
	v_lshl_add_u32 v22, v22, 1, v60
	ds_write_b16 v22, v2 offset:55296
	ds_write_b16_d16_hi v22, v2 offset:56080
	ds_write_b16 v22, v3 offset:56864
	ds_write_b16_d16_hi v22, v3 offset:57648
	ds_write_b16 v22, v4 offset:58432
	ds_write_b16_d16_hi v22, v4 offset:59216
	ds_write_b16 v22, v5 offset:60000
	ds_write_b16_d16_hi v22, v5 offset:60784
	v_mad_u64_u32 v[2:3], s[4:5], v51, s1, v[56:57]
	ds_write_b128 v2, v[30:33]
	v_xor_b32_e32 v2, v51, v57
	v_lshl_add_u32 v2, v2, 1, v60
	ds_write_b16 v2, v6 offset:55296
	ds_write_b16_d16_hi v2, v6 offset:56080
	ds_write_b16 v2, v7 offset:56864
	ds_write_b16_d16_hi v2, v7 offset:57648
	ds_write_b16 v2, v8 offset:58432
	ds_write_b16_d16_hi v2, v8 offset:59216
	ds_write_b16 v2, v9 offset:60000
	ds_write_b16_d16_hi v2, v9 offset:60784
	v_mad_u64_u32 v[2:3], s[4:5], v52, s1, v[56:57]
	ds_write_b128 v2, v[34:37]
	v_xor_b32_e32 v2, v52, v57
	v_lshl_add_u32 v2, v2, 1, v60
	ds_write_b16 v2, v10 offset:55296
	ds_write_b16_d16_hi v2, v10 offset:56080
	ds_write_b16 v2, v11 offset:56864
	ds_write_b16_d16_hi v2, v11 offset:57648
	ds_write_b16 v2, v12 offset:58432
	ds_write_b16_d16_hi v2, v12 offset:59216
	ds_write_b16 v2, v13 offset:60000
	ds_write_b16_d16_hi v2, v13 offset:60784
	v_mad_u64_u32 v[2:3], s[4:5], v53, s1, v[56:57]
	ds_write_b128 v2, v[38:41]
	v_xor_b32_e32 v2, v53, v57
	v_lshl_add_u32 v2, v2, 1, v60
	ds_write_b16 v2, v14 offset:55296
	ds_write_b16_d16_hi v2, v14 offset:56080
	ds_write_b16 v2, v15 offset:56864
	ds_write_b16_d16_hi v2, v15 offset:57648
	ds_write_b16 v2, v16 offset:58432
	ds_write_b16_d16_hi v2, v16 offset:59216
	ds_write_b16 v2, v17 offset:60000
	ds_write_b16_d16_hi v2, v17 offset:60784
	v_mad_u64_u32 v[2:3], s[4:5], v54, s1, v[56:57]
	ds_write_b128 v2, v[42:45]
	v_xor_b32_e32 v2, v54, v57
	v_lshl_add_u32 v2, v2, 1, v60
	ds_write_b16 v2, v18 offset:55296
	ds_write_b16_d16_hi v2, v18 offset:56080
	ds_write_b16 v2, v19 offset:56864
	ds_write_b16_d16_hi v2, v19 offset:57648
	ds_write_b16 v2, v20 offset:58432
	ds_write_b16_d16_hi v2, v20 offset:59216
	ds_write_b16 v2, v21 offset:60000
	ds_write_b16_d16_hi v2, v21 offset:60784
	v_mad_u64_u32 v[2:3], s[4:5], v55, s1, v[56:57]
	ds_write_b128 v2, v[46:49]
	v_xor_b32_e32 v2, v55, v57
	v_lshl_add_u32 v2, v2, 1, v60
	ds_write_b16 v2, v26 offset:55296
	ds_write_b16_d16_hi v2, v26 offset:56080
	ds_write_b16 v2, v27 offset:56864
	ds_write_b16_d16_hi v2, v27 offset:57648
	ds_write_b16 v2, v28 offset:58432
	ds_write_b16_d16_hi v2, v28 offset:59216
	ds_write_b16 v2, v29 offset:60000
	ds_write_b16_d16_hi v2, v29 offset:60784
	v_or_b32_e32 v2, s0, v101
	v_mul_lo_u32 v2, v2, s1
	s_movk_i32 s1, 0x100
	v_add3_u32 v0, s1, v0, v2
	s_waitcnt lgkmcnt(0)
	s_barrier
	v_lshlrev_b32_e32 v183, 2, v100
	v_sub_u32_e32 v183, v101, v183
	v_add_u32_e32 v184, 0x80, v183
	v_min_u32_e32 v185, 0x80, v98
	v_sub_u32_e32 v186, v184, v185
	v_lshlrev_b32_e32 v182, 2, v183
	v_add_u32_e32 v182, 0x19c94, v182
	s_ashr_i32 s15, s14, 31
	v_readfirstlane_b32 s4, v98
	s_mov_b32 s1, 0x3e38aa3b
	v_add_u32_e32 v198, 0, v101
	v_bfe_u32 v199, v198, 3, 3
	v_lshlrev_b32_e32 v199, 2, v199
	v_mul_u32_u24_e32 v198, 0x310, v198
	v_lshl_add_u32 v198, s0, 1, v198
	v_lshl_add_u32 v190, v100, 2, 0
	v_xor_b32_e32 v190, v190, v199
	v_lshl_add_u32 v190, v190, 1, v198
	v_lshl_add_u32 v191, v100, 2, 8
	v_xor_b32_e32 v191, v191, v199
	v_lshl_add_u32 v191, v191, 1, v198
	v_lshl_add_u32 v192, v100, 2, 16
	v_xor_b32_e32 v192, v192, v199
	v_lshl_add_u32 v192, v192, 1, v198
	v_lshl_add_u32 v193, v100, 2, 24
	v_xor_b32_e32 v193, v193, v199
	v_lshl_add_u32 v193, v193, 1, v198
	v_add_u32_e32 v198, 32, v101
	v_bfe_u32 v199, v198, 3, 3
	v_lshlrev_b32_e32 v199, 2, v199
	v_mul_u32_u24_e32 v198, 0x310, v198
	v_lshl_add_u32 v198, s0, 1, v198
	v_lshl_add_u32 v194, v100, 2, 0
	v_xor_b32_e32 v194, v194, v199
	v_lshl_add_u32 v194, v194, 1, v198
	v_lshl_add_u32 v195, v100, 2, 8
	v_xor_b32_e32 v195, v195, v199
	v_lshl_add_u32 v195, v195, 1, v198
	v_lshl_add_u32 v196, v100, 2, 16
	v_xor_b32_e32 v196, v196, v199
	v_lshl_add_u32 v196, v196, 1, v198
	v_lshl_add_u32 v197, v100, 2, 24
	v_xor_b32_e32 v197, v197, v199
	v_lshl_add_u32 v197, v197, 1, v198
	s_cmp_ge_u32 s4, 0x80
	s_cselect_b32 s5, 1, 0
	v_mov_b32_e32 v187, v239
	ds_read_b128 v[2:5], v0 offset:0
	ds_read_b128 v[6:9], v0 offset:32
	ds_read_b128 v[10:13], v0 offset:64
	ds_read_b128 v[14:17], v0 offset:96
	ds_read2_b32 v[34:35], v182 offset0:155 offset1:154
	ds_read2_b32 v[36:37], v182 offset0:153 offset1:152
	ds_read2_b32 v[38:39], v182 offset0:147 offset1:146
	ds_read2_b32 v[40:41], v182 offset0:145 offset1:144
	ds_read2_b32 v[42:43], v182 offset0:139 offset1:138
	ds_read2_b32 v[44:45], v182 offset0:137 offset1:136
	ds_read2_b32 v[46:47], v182 offset0:131 offset1:130
	ds_read2_b32 v[48:49], v182 offset0:129 offset1:128
	s_waitcnt lgkmcnt(0)
	v_mfma_f32_32x32x16_bf16 v[102:117], v[2:5], v[66:69], 0
	v_mfma_f32_32x32x16_bf16 v[102:117], v[6:9], v[90:93], v[102:117]
	v_mfma_f32_32x32x16_bf16 v[102:117], v[10:13], v[86:89], v[102:117]
	v_mfma_f32_32x32x16_bf16 v[102:117], v[14:17], v[82:85], v[102:117]
	ds_read_b128 v[2:5], v0 offset:4608
	ds_read_b128 v[6:9], v0 offset:4640
	ds_read_b128 v[10:13], v0 offset:4672
	ds_read_b128 v[14:17], v0 offset:4704
	ds_read2_b32 v[50:51], v182 offset0:123 offset1:122
	ds_read2_b32 v[52:53], v182 offset0:121 offset1:120
	ds_read2_b32 v[54:55], v182 offset0:115 offset1:114
	ds_read2_b32 v[56:57], v182 offset0:113 offset1:112
	ds_read2_b32 v[58:59], v182 offset0:107 offset1:106
	ds_read2_b32 v[60:61], v182 offset0:105 offset1:104
	ds_read2_b32 v[62:63], v182 offset0:99 offset1:98
	ds_read2_b32 v[64:65], v182 offset0:97 offset1:96
	s_waitcnt lgkmcnt(0)
; #define LAS __attribute__((address_space(3)))
; DI int crow(int i, int hh) { return (i & 3) + 8 * (i >> 2) + 4 * hh; }
; #define MFMA32(a, b, c) __builtin_amdgcn_mfma_f32_32x32x16_bf16((a), (b), (c), 0, 0, 0)
; DI void attn_dil_unit(LAS unsigned char* lds, const AttnArgs a) {
;     ...
;     for (int j = 0; j < 5; ++j) {
; #pragma unroll
;         for (int i = 0; i < 16; ++i) sc[j][i] = 0.f;
; #pragma unroll
;         for (int ks = 0; ks < 4; ++ks) {
;             const bf16x8 kf = *(const LAS bf16x8*)(Kl + (32 * wid + 32 * j + r32) * KLD + ks * 16 + 8 * hh);
;             sc[j] = MFMA32(kf, qf[ks], sc[j]);
;         }
;     }
;     float mx = -1e30f;
; #pragma unroll
;     for (int j = 0; j < 5; ++j)
; #pragma unroll
;         for (int i = 0; i < 16; ++i) {
;             const int st = r32 + 128 - 32 * j - crow(i, hh);
;             const int kj = qi - st;
;             const bool valid = (st >= 0) && (st <= 128) && (kj >= 0);
;             float x = sc[j][i] * a.c2 + biasL[min(max(st, 0), 128)];
;             x = valid ? x : -1e30f;
;             sc[j][i] = x; mx = fmaxf(mx, x);
;         }
	v_mfma_f32_32x32x16_bf16 v[118:133], v[2:5], v[66:69], 0
	v_mfma_f32_32x32x16_bf16 v[118:133], v[6:9], v[90:93], v[118:133]
	v_mfma_f32_32x32x16_bf16 v[118:133], v[10:13], v[86:89], v[118:133]
	v_mfma_f32_32x32x16_bf16 v[118:133], v[14:17], v[82:85], v[118:133]
	ds_read_b128 v[2:5], v0 offset:9216
	ds_read_b128 v[6:9], v0 offset:9248
	ds_read_b128 v[10:13], v0 offset:9280
	ds_read_b128 v[14:17], v0 offset:9312
	v_fma_f32 v102, v102, s1, v34
	v_fma_f32 v103, v103, s1, v35
	v_fma_f32 v104, v104, s1, v36
	v_fma_f32 v105, v105, s1, v37
	v_fma_f32 v106, v106, s1, v38
	v_fma_f32 v107, v107, s1, v39
	v_fma_f32 v108, v108, s1, v40
	v_fma_f32 v109, v109, s1, v41
	v_fma_f32 v110, v110, s1, v42
	v_fma_f32 v111, v111, s1, v43
	v_fma_f32 v112, v112, s1, v44
	v_fma_f32 v113, v113, s1, v45
	v_fma_f32 v114, v114, s1, v46
	v_fma_f32 v115, v115, s1, v47
	v_fma_f32 v116, v116, s1, v48
	v_fma_f32 v117, v117, s1, v49
	v_sub_u32_e32 v198, 0, v186
	v_sub_u32_e32 v199, 1, v186
	v_sub_u32_e32 v188, 2, v186
	v_sub_u32_e32 v189, 3, v186
	v_cmp_ge_u32_e64 s[6:7], v185, v198
	v_cmp_ge_u32_e64 s[8:9], v185, v199
	v_cmp_ge_u32_e64 s[10:11], v185, v188
	v_cmp_ge_u32_e64 s[12:13], v185, v189
	v_cndmask_b32_e64 v102, v239, v102, s[6:7]
	v_cndmask_b32_e64 v103, v239, v103, s[8:9]
	v_cndmask_b32_e64 v104, v239, v104, s[10:11]
	v_cndmask_b32_e64 v105, v239, v105, s[12:13]
	v_sub_u32_e32 v198, 8, v186
	v_sub_u32_e32 v199, 9, v186
	v_sub_u32_e32 v188, 10, v186
	v_sub_u32_e32 v189, 11, v186
	v_cmp_ge_u32_e64 s[6:7], v185, v198
	v_cmp_ge_u32_e64 s[8:9], v185, v199
	v_cmp_ge_u32_e64 s[10:11], v185, v188
	v_cmp_ge_u32_e64 s[12:13], v185, v189
	v_cndmask_b32_e64 v106, v239, v106, s[6:7]
	v_cndmask_b32_e64 v107, v239, v107, s[8:9]
	v_cndmask_b32_e64 v108, v239, v108, s[10:11]
	v_cndmask_b32_e64 v109, v239, v109, s[12:13]
	v_sub_u32_e32 v198, 16, v186
	v_sub_u32_e32 v199, 17, v186
	v_sub_u32_e32 v188, 18, v186
	v_sub_u32_e32 v189, 19, v186
	v_cmp_ge_u32_e64 s[6:7], v185, v198
	v_cmp_ge_u32_e64 s[8:9], v185, v199
	v_cmp_ge_u32_e64 s[10:11], v185, v188
	v_cmp_ge_u32_e64 s[12:13], v185, v189
	v_cndmask_b32_e64 v110, v239, v110, s[6:7]
	v_cndmask_b32_e64 v111, v239, v111, s[8:9]
	v_cndmask_b32_e64 v112, v239, v112, s[10:11]
	v_cndmask_b32_e64 v113, v239, v113, s[12:13]
	v_sub_u32_e32 v198, 24, v186
	v_sub_u32_e32 v199, 25, v186
	v_sub_u32_e32 v188, 26, v186
	v_sub_u32_e32 v189, 27, v186
	v_cmp_ge_u32_e64 s[6:7], v185, v198
	v_cmp_ge_u32_e64 s[8:9], v185, v199
	v_cmp_ge_u32_e64 s[10:11], v185, v188
	v_cmp_ge_u32_e64 s[12:13], v185, v189
	v_cndmask_b32_e64 v114, v239, v114, s[6:7]
	v_cndmask_b32_e64 v115, v239, v115, s[8:9]
	v_cndmask_b32_e64 v116, v239, v116, s[10:11]
	v_cndmask_b32_e64 v117, v239, v117, s[12:13]
	v_max3_f32 v187, v187, v102, v103
	v_max3_f32 v187, v187, v104, v105
	v_max3_f32 v187, v187, v106, v107
	v_max3_f32 v187, v187, v108, v109
	v_max3_f32 v187, v187, v110, v111
	v_max3_f32 v187, v187, v112, v113
	v_max3_f32 v187, v187, v114, v115
	v_max3_f32 v187, v187, v116, v117
	ds_read2_b32 v[34:35], v182 offset0:91 offset1:90
	ds_read2_b32 v[36:37], v182 offset0:89 offset1:88
	ds_read2_b32 v[38:39], v182 offset0:83 offset1:82
	ds_read2_b32 v[40:41], v182 offset0:81 offset1:80
	ds_read2_b32 v[42:43], v182 offset0:75 offset1:74
	ds_read2_b32 v[44:45], v182 offset0:73 offset1:72
	ds_read2_b32 v[46:47], v182 offset0:67 offset1:66
	ds_read2_b32 v[48:49], v182 offset0:65 offset1:64
	s_waitcnt lgkmcnt(0)
	v_mfma_f32_32x32x16_bf16 v[134:149], v[2:5], v[66:69], 0
	v_mfma_f32_32x32x16_bf16 v[134:149], v[6:9], v[90:93], v[134:149]
	v_mfma_f32_32x32x16_bf16 v[134:149], v[10:13], v[86:89], v[134:149]
	v_mfma_f32_32x32x16_bf16 v[134:149], v[14:17], v[82:85], v[134:149]
	ds_read_b128 v[2:5], v0 offset:13824
	ds_read_b128 v[6:9], v0 offset:13856
	ds_read_b128 v[10:13], v0 offset:13888
	ds_read_b128 v[14:17], v0 offset:13920
	v_subrev_u32_e32 v186, 32, v186
	v_fma_f32 v118, v118, s1, v50
	v_fma_f32 v119, v119, s1, v51
	v_fma_f32 v120, v120, s1, v52
	v_fma_f32 v121, v121, s1, v53
	v_fma_f32 v122, v122, s1, v54
	v_fma_f32 v123, v123, s1, v55
	v_fma_f32 v124, v124, s1, v56
	v_fma_f32 v125, v125, s1, v57
	v_fma_f32 v126, v126, s1, v58
	v_fma_f32 v127, v127, s1, v59
	v_fma_f32 v128, v128, s1, v60
	v_fma_f32 v129, v129, s1, v61
	v_fma_f32 v130, v130, s1, v62
	v_fma_f32 v131, v131, s1, v63
	v_fma_f32 v132, v132, s1, v64
	v_fma_f32 v133, v133, s1, v65
	s_cmp_lg_u32 s5, 0
	s_cbranch_scc1 .Ldil_nomask1
	v_sub_u32_e32 v198, 0, v186
	v_sub_u32_e32 v199, 1, v186
	v_sub_u32_e32 v188, 2, v186
	v_sub_u32_e32 v189, 3, v186
	v_cmp_ge_u32_e64 s[6:7], v185, v198
	v_cmp_ge_u32_e64 s[8:9], v185, v199
	v_cmp_ge_u32_e64 s[10:11], v185, v188
	v_cmp_ge_u32_e64 s[12:13], v185, v189
	v_cndmask_b32_e64 v118, v239, v118, s[6:7]
	v_cndmask_b32_e64 v119, v239, v119, s[8:9]
	v_cndmask_b32_e64 v120, v239, v120, s[10:11]
	v_cndmask_b32_e64 v121, v239, v121, s[12:13]
	v_sub_u32_e32 v198, 8, v186
	v_sub_u32_e32 v199, 9, v186
	v_sub_u32_e32 v188, 10, v186
	v_sub_u32_e32 v189, 11, v186
	v_cmp_ge_u32_e64 s[6:7], v185, v198
	v_cmp_ge_u32_e64 s[8:9], v185, v199
	v_cmp_ge_u32_e64 s[10:11], v185, v188
	v_cmp_ge_u32_e64 s[12:13], v185, v189
	v_cndmask_b32_e64 v122, v239, v122, s[6:7]
	v_cndmask_b32_e64 v123, v239, v123, s[8:9]
	v_cndmask_b32_e64 v124, v239, v124, s[10:11]
	v_cndmask_b32_e64 v125, v239, v125, s[12:13]
	v_sub_u32_e32 v198, 16, v186
	v_sub_u32_e32 v199, 17, v186
	v_sub_u32_e32 v188, 18, v186
	v_sub_u32_e32 v189, 19, v186
	v_cmp_ge_u32_e64 s[6:7], v185, v198
	v_cmp_ge_u32_e64 s[8:9], v185, v199
	v_cmp_ge_u32_e64 s[10:11], v185, v188
	v_cmp_ge_u32_e64 s[12:13], v185, v189
	v_cndmask_b32_e64 v126, v239, v126, s[6:7]
	v_cndmask_b32_e64 v127, v239, v127, s[8:9]
	v_cndmask_b32_e64 v128, v239, v128, s[10:11]
	v_cndmask_b32_e64 v129, v239, v129, s[12:13]
	v_sub_u32_e32 v198, 24, v186
	v_sub_u32_e32 v199, 25, v186
	v_sub_u32_e32 v188, 26, v186
	v_sub_u32_e32 v189, 27, v186
	v_cmp_ge_u32_e64 s[6:7], v185, v198
	v_cmp_ge_u32_e64 s[8:9], v185, v199
	v_cmp_ge_u32_e64 s[10:11], v185, v188
	v_cmp_ge_u32_e64 s[12:13], v185, v189
	v_cndmask_b32_e64 v130, v239, v130, s[6:7]
	v_cndmask_b32_e64 v131, v239, v131, s[8:9]
	v_cndmask_b32_e64 v132, v239, v132, s[10:11]
	v_cndmask_b32_e64 v133, v239, v133, s[12:13]
; #define LAS __attribute__((address_space(3)))
; DI int crow(int i, int hh) { return (i & 3) + 8 * (i >> 2) + 4 * hh; }
; #define MFMA32(a, b, c) __builtin_amdgcn_mfma_f32_32x32x16_bf16((a), (b), (c), 0, 0, 0)
; DI void attn_dil_unit(LAS unsigned char* lds, const AttnArgs a) {
;     ...
;     for (int j = 0; j < 5; ++j) {
; #pragma unroll
;         for (int i = 0; i < 16; ++i) sc[j][i] = 0.f;
; #pragma unroll
;         for (int ks = 0; ks < 4; ++ks) {
;             const bf16x8 kf = *(const LAS bf16x8*)(Kl + (32 * wid + 32 * j + r32) * KLD + ks * 16 + 8 * hh);
;             sc[j] = MFMA32(kf, qf[ks], sc[j]);
;         }
;     }
;     float mx = -1e30f;
; #pragma unroll
;     for (int j = 0; j < 5; ++j)
; #pragma unroll
;         for (int i = 0; i < 16; ++i) {
;             const int st = r32 + 128 - 32 * j - crow(i, hh);
;             const int kj = qi - st;
;             const bool valid = (st >= 0) && (st <= 128) && (kj >= 0);
;             float x = sc[j][i] * a.c2 + biasL[min(max(st, 0), 128)];
;             x = valid ? x : -1e30f;
;             sc[j][i] = x; mx = fmaxf(mx, x);
;         }
.Ldil_nomask1:
	v_max3_f32 v187, v187, v118, v119
	v_max3_f32 v187, v187, v120, v121
	v_max3_f32 v187, v187, v122, v123
	v_max3_f32 v187, v187, v124, v125
	v_max3_f32 v187, v187, v126, v127
	v_max3_f32 v187, v187, v128, v129
	v_max3_f32 v187, v187, v130, v131
	v_max3_f32 v187, v187, v132, v133
	ds_read2_b32 v[50:51], v182 offset0:59 offset1:58
	ds_read2_b32 v[52:53], v182 offset0:57 offset1:56
	ds_read2_b32 v[54:55], v182 offset0:51 offset1:50
	ds_read2_b32 v[56:57], v182 offset0:49 offset1:48
	ds_read2_b32 v[58:59], v182 offset0:43 offset1:42
	ds_read2_b32 v[60:61], v182 offset0:41 offset1:40
	ds_read2_b32 v[62:63], v182 offset0:35 offset1:34
	ds_read2_b32 v[64:65], v182 offset0:33 offset1:32
	s_waitcnt lgkmcnt(0)
	v_mfma_f32_32x32x16_bf16 v[150:165], v[2:5], v[66:69], 0
	v_mfma_f32_32x32x16_bf16 v[150:165], v[6:9], v[90:93], v[150:165]
	v_mfma_f32_32x32x16_bf16 v[150:165], v[10:13], v[86:89], v[150:165]
	v_mfma_f32_32x32x16_bf16 v[150:165], v[14:17], v[82:85], v[150:165]
	ds_read_b128 v[2:5], v0 offset:18432
	ds_read_b128 v[6:9], v0 offset:18464
	ds_read_b128 v[10:13], v0 offset:18496
	ds_read_b128 v[14:17], v0 offset:18528
	v_subrev_u32_e32 v186, 32, v186
	v_fma_f32 v134, v134, s1, v34
	v_fma_f32 v135, v135, s1, v35
	v_fma_f32 v136, v136, s1, v36
	v_fma_f32 v137, v137, s1, v37
	v_fma_f32 v138, v138, s1, v38
	v_fma_f32 v139, v139, s1, v39
	v_fma_f32 v140, v140, s1, v40
	v_fma_f32 v141, v141, s1, v41
	v_fma_f32 v142, v142, s1, v42
	v_fma_f32 v143, v143, s1, v43
	v_fma_f32 v144, v144, s1, v44
	v_fma_f32 v145, v145, s1, v45
	v_fma_f32 v146, v146, s1, v46
	v_fma_f32 v147, v147, s1, v47
	v_fma_f32 v148, v148, s1, v48
	v_fma_f32 v149, v149, s1, v49
	s_cmp_lg_u32 s5, 0
	s_cbranch_scc1 .Ldil_nomask2
	v_sub_u32_e32 v198, 0, v186
	v_sub_u32_e32 v199, 1, v186
	v_sub_u32_e32 v188, 2, v186
	v_sub_u32_e32 v189, 3, v186
	v_cmp_ge_u32_e64 s[6:7], v185, v198
	v_cmp_ge_u32_e64 s[8:9], v185, v199
	v_cmp_ge_u32_e64 s[10:11], v185, v188
	v_cmp_ge_u32_e64 s[12:13], v185, v189
	v_cndmask_b32_e64 v134, v239, v134, s[6:7]
	v_cndmask_b32_e64 v135, v239, v135, s[8:9]
	v_cndmask_b32_e64 v136, v239, v136, s[10:11]
	v_cndmask_b32_e64 v137, v239, v137, s[12:13]
	v_sub_u32_e32 v198, 8, v186
	v_sub_u32_e32 v199, 9, v186
	v_sub_u32_e32 v188, 10, v186
	v_sub_u32_e32 v189, 11, v186
	v_cmp_ge_u32_e64 s[6:7], v185, v198
	v_cmp_ge_u32_e64 s[8:9], v185, v199
	v_cmp_ge_u32_e64 s[10:11], v185, v188
	v_cmp_ge_u32_e64 s[12:13], v185, v189
	v_cndmask_b32_e64 v138, v239, v138, s[6:7]
	v_cndmask_b32_e64 v139, v239, v139, s[8:9]
	v_cndmask_b32_e64 v140, v239, v140, s[10:11]
	v_cndmask_b32_e64 v141, v239, v141, s[12:13]
	v_sub_u32_e32 v198, 16, v186
	v_sub_u32_e32 v199, 17, v186
	v_sub_u32_e32 v188, 18, v186
	v_sub_u32_e32 v189, 19, v186
	v_cmp_ge_u32_e64 s[6:7], v185, v198
	v_cmp_ge_u32_e64 s[8:9], v185, v199
	v_cmp_ge_u32_e64 s[10:11], v185, v188
	v_cmp_ge_u32_e64 s[12:13], v185, v189
	v_cndmask_b32_e64 v142, v239, v142, s[6:7]
	v_cndmask_b32_e64 v143, v239, v143, s[8:9]
	v_cndmask_b32_e64 v144, v239, v144, s[10:11]
	v_cndmask_b32_e64 v145, v239, v145, s[12:13]
	v_sub_u32_e32 v198, 24, v186
	v_sub_u32_e32 v199, 25, v186
	v_sub_u32_e32 v188, 26, v186
	v_sub_u32_e32 v189, 27, v186
	v_cmp_ge_u32_e64 s[6:7], v185, v198
	v_cmp_ge_u32_e64 s[8:9], v185, v199
	v_cmp_ge_u32_e64 s[10:11], v185, v188
	v_cmp_ge_u32_e64 s[12:13], v185, v189
	v_cndmask_b32_e64 v146, v239, v146, s[6:7]
	v_cndmask_b32_e64 v147, v239, v147, s[8:9]
	v_cndmask_b32_e64 v148, v239, v148, s[10:11]
	v_cndmask_b32_e64 v149, v239, v149, s[12:13]
.Ldil_nomask2:
	v_max3_f32 v187, v187, v134, v135
	v_max3_f32 v187, v187, v136, v137
	v_max3_f32 v187, v187, v138, v139
	v_max3_f32 v187, v187, v140, v141
	v_max3_f32 v187, v187, v142, v143
	v_max3_f32 v187, v187, v144, v145
	v_max3_f32 v187, v187, v146, v147
	v_max3_f32 v187, v187, v148, v149
	ds_read2_b32 v[34:35], v182 offset0:27 offset1:26
	ds_read2_b32 v[36:37], v182 offset0:25 offset1:24
	ds_read2_b32 v[38:39], v182 offset0:19 offset1:18
	ds_read2_b32 v[40:41], v182 offset0:17 offset1:16
	ds_read2_b32 v[42:43], v182 offset0:11 offset1:10
	ds_read2_b32 v[44:45], v182 offset0:9 offset1:8
	ds_read2_b32 v[46:47], v182 offset0:3 offset1:2
	ds_read2_b32 v[48:49], v182 offset0:1 offset1:0
	s_waitcnt lgkmcnt(0)
	v_mfma_f32_32x32x16_bf16 v[166:181], v[2:5], v[66:69], 0
	v_mfma_f32_32x32x16_bf16 v[166:181], v[6:9], v[90:93], v[166:181]
	v_mfma_f32_32x32x16_bf16 v[166:181], v[10:13], v[86:89], v[166:181]
	v_mfma_f32_32x32x16_bf16 v[166:181], v[14:17], v[82:85], v[166:181]
	v_subrev_u32_e32 v186, 32, v186
	v_fma_f32 v150, v150, s1, v50
	v_fma_f32 v151, v151, s1, v51
	v_fma_f32 v152, v152, s1, v52
	v_fma_f32 v153, v153, s1, v53
	v_fma_f32 v154, v154, s1, v54
	v_fma_f32 v155, v155, s1, v55
	v_fma_f32 v156, v156, s1, v56
	v_fma_f32 v157, v157, s1, v57
	v_fma_f32 v158, v158, s1, v58
	v_fma_f32 v159, v159, s1, v59
	v_fma_f32 v160, v160, s1, v60
	v_fma_f32 v161, v161, s1, v61
	v_fma_f32 v162, v162, s1, v62
	v_fma_f32 v163, v163, s1, v63
	v_fma_f32 v164, v164, s1, v64
	v_fma_f32 v165, v165, s1, v65
	s_cmp_lg_u32 s5, 0
	s_cbranch_scc1 .Ldil_nomask3
	v_sub_u32_e32 v198, 0, v186
	v_sub_u32_e32 v199, 1, v186
	v_sub_u32_e32 v188, 2, v186
	v_sub_u32_e32 v189, 3, v186
	v_cmp_ge_u32_e64 s[6:7], v185, v198
	v_cmp_ge_u32_e64 s[8:9], v185, v199
	v_cmp_ge_u32_e64 s[10:11], v185, v188
	v_cmp_ge_u32_e64 s[12:13], v185, v189
	v_cndmask_b32_e64 v150, v239, v150, s[6:7]
	v_cndmask_b32_e64 v151, v239, v151, s[8:9]
	v_cndmask_b32_e64 v152, v239, v152, s[10:11]
	v_cndmask_b32_e64 v153, v239, v153, s[12:13]
	v_sub_u32_e32 v198, 8, v186
	v_sub_u32_e32 v199, 9, v186
	v_sub_u32_e32 v188, 10, v186
	v_sub_u32_e32 v189, 11, v186
	v_cmp_ge_u32_e64 s[6:7], v185, v198
	v_cmp_ge_u32_e64 s[8:9], v185, v199
	v_cmp_ge_u32_e64 s[10:11], v185, v188
	v_cmp_ge_u32_e64 s[12:13], v185, v189
	v_cndmask_b32_e64 v154, v239, v154, s[6:7]
	v_cndmask_b32_e64 v155, v239, v155, s[8:9]
	v_cndmask_b32_e64 v156, v239, v156, s[10:11]
	v_cndmask_b32_e64 v157, v239, v157, s[12:13]
	v_sub_u32_e32 v198, 16, v186
	v_sub_u32_e32 v199, 17, v186
	v_sub_u32_e32 v188, 18, v186
	v_sub_u32_e32 v189, 19, v186
	v_cmp_ge_u32_e64 s[6:7], v185, v198
	v_cmp_ge_u32_e64 s[8:9], v185, v199
	v_cmp_ge_u32_e64 s[10:11], v185, v188
	v_cmp_ge_u32_e64 s[12:13], v185, v189
	v_cndmask_b32_e64 v158, v239, v158, s[6:7]
	v_cndmask_b32_e64 v159, v239, v159, s[8:9]
	v_cndmask_b32_e64 v160, v239, v160, s[10:11]
	v_cndmask_b32_e64 v161, v239, v161, s[12:13]
	v_sub_u32_e32 v198, 24, v186
	v_sub_u32_e32 v199, 25, v186
	v_sub_u32_e32 v188, 26, v186
	v_sub_u32_e32 v189, 27, v186
	v_cmp_ge_u32_e64 s[6:7], v185, v198
	v_cmp_ge_u32_e64 s[8:9], v185, v199
	v_cmp_ge_u32_e64 s[10:11], v185, v188
	v_cmp_ge_u32_e64 s[12:13], v185, v189
	v_cndmask_b32_e64 v162, v239, v162, s[6:7]
	v_cndmask_b32_e64 v163, v239, v163, s[8:9]
	v_cndmask_b32_e64 v164, v239, v164, s[10:11]
	v_cndmask_b32_e64 v165, v239, v165, s[12:13]
; DI float ex2(float x) { return __builtin_amdgcn_exp2f(x); }
; DI int crow(int i, int hh) { return (i & 3) + 8 * (i >> 2) + 4 * hh; }
; DI void attn_dil_unit(LAS unsigned char* lds, const AttnArgs a) {
;     ...
;     float mx = -1e30f;
; #pragma unroll
;     for (int j = 0; j < 5; ++j)
; #pragma unroll
;         for (int i = 0; i < 16; ++i) {
;             const int st = r32 + 128 - 32 * j - crow(i, hh);
;             const int kj = qi - st;
;             const bool valid = (st >= 0) && (st <= 128) && (kj >= 0);
;             float x = sc[j][i] * a.c2 + biasL[min(max(st, 0), 128)];
;             x = valid ? x : -1e30f;
;             sc[j][i] = x; mx = fmaxf(mx, x);
;         }
;     mx = fmaxf(mx, __shfl_xor(mx, 32));
;     float ls = 0.f;
; #pragma unroll
;     for (int j = 0; j < 5; ++j)
; #pragma unroll
;         for (int i = 0; i < 16; ++i) { const float p = (sc[j][i] > -1e29f) ? ex2(sc[j][i] - mx) : 0.f; sc[j][i] = p; ls += p; }
;     const float lt = ls + __shfl_xor(ls, 32);
;     f32x16 o[2];
; #pragma unroll
;     for (int d = 0; d < 2; ++d)
; #pragma unroll
;         for (int i = 0; i < 16; ++i) o[d][i] = 0.f;
; #pragma unroll
;     for (int j = 0; j < 5; ++j) {
;         const bf16x8 pb0 = pack8(sc[j], 0), pb1 = pack8(sc[j], 1);
.Ldil_nomask3:
	v_max3_f32 v187, v187, v150, v151
	v_max3_f32 v187, v187, v152, v153
	v_max3_f32 v187, v187, v154, v155
	v_max3_f32 v187, v187, v156, v157
	v_max3_f32 v187, v187, v158, v159
	v_max3_f32 v187, v187, v160, v161
	v_max3_f32 v187, v187, v162, v163
	v_max3_f32 v187, v187, v164, v165
	s_waitcnt lgkmcnt(0)
	v_subrev_u32_e32 v186, 32, v186
	v_fma_f32 v166, v166, s1, v34
	v_fma_f32 v167, v167, s1, v35
	v_fma_f32 v168, v168, s1, v36
	v_fma_f32 v169, v169, s1, v37
	v_fma_f32 v170, v170, s1, v38
	v_fma_f32 v171, v171, s1, v39
	v_fma_f32 v172, v172, s1, v40
	v_fma_f32 v173, v173, s1, v41
	v_fma_f32 v174, v174, s1, v42
	v_fma_f32 v175, v175, s1, v43
	v_fma_f32 v176, v176, s1, v44
	v_fma_f32 v177, v177, s1, v45
	v_fma_f32 v178, v178, s1, v46
	v_fma_f32 v179, v179, s1, v47
	v_fma_f32 v180, v180, s1, v48
	v_fma_f32 v181, v181, s1, v49
	v_sub_u32_e32 v198, 0, v186
	v_sub_u32_e32 v199, 1, v186
	v_sub_u32_e32 v188, 2, v186
	v_sub_u32_e32 v189, 3, v186
	v_cmp_ge_u32_e64 s[6:7], v185, v198
	v_cmp_ge_u32_e64 s[8:9], v185, v199
	v_cmp_ge_u32_e64 s[10:11], v185, v188
	v_cmp_ge_u32_e64 s[12:13], v185, v189
	v_cndmask_b32_e64 v166, v239, v166, s[6:7]
	v_cndmask_b32_e64 v167, v239, v167, s[8:9]
	v_cndmask_b32_e64 v168, v239, v168, s[10:11]
	v_cndmask_b32_e64 v169, v239, v169, s[12:13]
	v_sub_u32_e32 v198, 8, v186
	v_sub_u32_e32 v199, 9, v186
	v_sub_u32_e32 v188, 10, v186
	v_sub_u32_e32 v189, 11, v186
	v_cmp_ge_u32_e64 s[6:7], v185, v198
	v_cmp_ge_u32_e64 s[8:9], v185, v199
	v_cmp_ge_u32_e64 s[10:11], v185, v188
	v_cmp_ge_u32_e64 s[12:13], v185, v189
	v_cndmask_b32_e64 v170, v239, v170, s[6:7]
	v_cndmask_b32_e64 v171, v239, v171, s[8:9]
	v_cndmask_b32_e64 v172, v239, v172, s[10:11]
	v_cndmask_b32_e64 v173, v239, v173, s[12:13]
	v_sub_u32_e32 v198, 16, v186
	v_sub_u32_e32 v199, 17, v186
	v_sub_u32_e32 v188, 18, v186
	v_sub_u32_e32 v189, 19, v186
	v_cmp_ge_u32_e64 s[6:7], v185, v198
	v_cmp_ge_u32_e64 s[8:9], v185, v199
	v_cmp_ge_u32_e64 s[10:11], v185, v188
	v_cmp_ge_u32_e64 s[12:13], v185, v189
	v_cndmask_b32_e64 v174, v239, v174, s[6:7]
	v_cndmask_b32_e64 v175, v239, v175, s[8:9]
	v_cndmask_b32_e64 v176, v239, v176, s[10:11]
	v_cndmask_b32_e64 v177, v239, v177, s[12:13]
	v_sub_u32_e32 v198, 24, v186
	v_sub_u32_e32 v199, 25, v186
	v_sub_u32_e32 v188, 26, v186
	v_sub_u32_e32 v189, 27, v186
	v_cmp_ge_u32_e64 s[6:7], v185, v198
	v_cmp_ge_u32_e64 s[8:9], v185, v199
	v_cmp_ge_u32_e64 s[10:11], v185, v188
	v_cmp_ge_u32_e64 s[12:13], v185, v189
	v_cndmask_b32_e64 v178, v239, v178, s[6:7]
	v_cndmask_b32_e64 v179, v239, v179, s[8:9]
	v_cndmask_b32_e64 v180, v239, v180, s[10:11]
	v_cndmask_b32_e64 v181, v239, v181, s[12:13]
	v_max3_f32 v187, v187, v166, v167
	v_max3_f32 v187, v187, v168, v169
	v_max3_f32 v187, v187, v170, v171
	v_max3_f32 v187, v187, v172, v173
	v_max3_f32 v187, v187, v174, v175
	v_max3_f32 v187, v187, v176, v177
	v_max3_f32 v187, v187, v178, v179
	v_max3_f32 v187, v187, v180, v181
	v_and_b32_e32 v198, 64, v243
	v_xor_b32_e32 v199, 32, v243
	v_add_u32_e32 v198, 64, v198
	v_cmp_lt_i32_e32 vcc, v199, v198
	s_nop 1
	v_cndmask_b32_e32 v199, v243, v199, vcc
	v_lshlrev_b32_e32 v199, 2, v199
	ds_bpermute_b32 v198, v199, v187
	ds_read_b64 v[34:35], v190 offset:55552
	ds_read_b64 v[36:37], v191 offset:55552
	ds_read_b64 v[38:39], v194 offset:55552
	ds_read_b64 v[40:41], v195 offset:55552
	ds_read_b64 v[42:43], v192 offset:55552
	ds_read_b64 v[44:45], v193 offset:55552
	ds_read_b64 v[46:47], v196 offset:55552
	ds_read_b64 v[48:49], v197 offset:55552
	s_waitcnt lgkmcnt(8)
	v_max_f32_e32 v88, v187, v198
	v_mov_b32_e32 v188, 0
	v_mov_b32_e32 v189, 0
	v_sub_f32_e32 v102, v102, v88
	v_sub_f32_e32 v103, v103, v88
	v_sub_f32_e32 v104, v104, v88
	v_sub_f32_e32 v105, v105, v88
	v_sub_f32_e32 v106, v106, v88
	v_sub_f32_e32 v107, v107, v88
	v_sub_f32_e32 v108, v108, v88
	v_sub_f32_e32 v109, v109, v88
	v_exp_f32_e32 v102, v102
	v_exp_f32_e32 v103, v103
	v_exp_f32_e32 v104, v104
	v_exp_f32_e32 v105, v105
	v_exp_f32_e32 v106, v106
	v_exp_f32_e32 v107, v107
	v_exp_f32_e32 v108, v108
	v_exp_f32_e32 v109, v109
	v_pk_add_f32 v[188:189], v[188:189], v[102:103]
	v_pk_add_f32 v[188:189], v[188:189], v[104:105]
	v_pk_add_f32 v[188:189], v[188:189], v[106:107]
	v_pk_add_f32 v[188:189], v[188:189], v[108:109]
	v_cvt_pk_bf16_f32 v102, v102, v103
	v_cvt_pk_bf16_f32 v103, v104, v105
	v_cvt_pk_bf16_f32 v104, v106, v107
	v_cvt_pk_bf16_f32 v105, v108, v109
	s_nop 1
	s_waitcnt lgkmcnt(4)
	v_mfma_f32_32x32x16_bf16 v[18:33], v[34:37], v[102:105], 0
	v_mfma_f32_32x32x16_bf16 v[2:17], v[38:41], v[102:105], 0
	ds_read_b64 v[34:35], v190 offset:55616
	ds_read_b64 v[36:37], v191 offset:55616
	ds_read_b64 v[38:39], v194 offset:55616
	ds_read_b64 v[40:41], v195 offset:55616
	v_sub_f32_e32 v110, v110, v88
	v_sub_f32_e32 v111, v111, v88
	v_sub_f32_e32 v112, v112, v88
	v_sub_f32_e32 v113, v113, v88
	v_sub_f32_e32 v114, v114, v88
	v_sub_f32_e32 v115, v115, v88
	v_sub_f32_e32 v116, v116, v88
	v_sub_f32_e32 v117, v117, v88
	v_exp_f32_e32 v110, v110
	v_exp_f32_e32 v111, v111
	v_exp_f32_e32 v112, v112
	v_exp_f32_e32 v113, v113
	v_exp_f32_e32 v114, v114
	v_exp_f32_e32 v115, v115
	v_exp_f32_e32 v116, v116
	v_exp_f32_e32 v117, v117
	v_pk_add_f32 v[188:189], v[188:189], v[110:111]
	v_pk_add_f32 v[188:189], v[188:189], v[112:113]
	v_pk_add_f32 v[188:189], v[188:189], v[114:115]
	v_pk_add_f32 v[188:189], v[188:189], v[116:117]
	v_cvt_pk_bf16_f32 v110, v110, v111
	v_cvt_pk_bf16_f32 v111, v112, v113
	v_cvt_pk_bf16_f32 v112, v114, v115
	v_cvt_pk_bf16_f32 v113, v116, v117
	s_nop 1
	s_waitcnt lgkmcnt(4)
; #define LAS __attribute__((address_space(3)))
; DI float ex2(float x) { return __builtin_amdgcn_exp2f(x); }
; #define MFMA32(a, b, c) __builtin_amdgcn_mfma_f32_32x32x16_bf16((a), (b), (c), 0, 0, 0)
; #define VFRAG2(off) __builtin_shufflevector(*(const LAS s16x4*)(vp + (((off) + 4 * hh) ^ sw)), *(const LAS s16x4*)(vp + (((off) + 8 + 4 * hh) ^ sw)), 0, 1, 2, 3, 4, 5, 6, 7)
; DI void attn_dil_unit(LAS unsigned char* lds, const AttnArgs a) {
;     ...
;     float ls = 0.f;
; #pragma unroll
;     for (int j = 0; j < 5; ++j)
; #pragma unroll
;         for (int i = 0; i < 16; ++i) { const float p = (sc[j][i] > -1e29f) ? ex2(sc[j][i] - mx) : 0.f; sc[j][i] = p; ls += p; }
;     const float lt = ls + __shfl_xor(ls, 32);
;     f32x16 o[2];
; #pragma unroll
;     for (int d = 0; d < 2; ++d)
; #pragma unroll
;         for (int i = 0; i < 16; ++i) o[d][i] = 0.f;
; #pragma unroll
;     for (int j = 0; j < 5; ++j) {
;         const bf16x8 pb0 = pack8(sc[j], 0), pb1 = pack8(sc[j], 1);
; #pragma unroll
;         for (int d = 0; d < 2; ++d) {
;             const LAS bf16_t* vp = Vl + (d * 32 + r32) * VLD + 32 * wid + 32 * j;
;             const int sw = (((d * 32 + r32) >> 3) & 7) << 2;
;     ...
;             o[d] = MFMA32(VFRAG2(0), pb0, o[d]);
;             o[d] = MFMA32(VFRAG2(16), pb1, o[d]);
;     ...
;         }
;     }
	v_mfma_f32_32x32x16_bf16 v[18:33], v[42:45], v[110:113], v[18:33]
	v_mfma_f32_32x32x16_bf16 v[2:17], v[46:49], v[110:113], v[2:17]
	ds_read_b64 v[42:43], v192 offset:55616
	ds_read_b64 v[44:45], v193 offset:55616
	ds_read_b64 v[46:47], v196 offset:55616
	ds_read_b64 v[48:49], v197 offset:55616
	v_sub_f32_e32 v118, v118, v88
	v_sub_f32_e32 v119, v119, v88
	v_sub_f32_e32 v120, v120, v88
	v_sub_f32_e32 v121, v121, v88
	v_sub_f32_e32 v122, v122, v88
	v_sub_f32_e32 v123, v123, v88
	v_sub_f32_e32 v124, v124, v88
	v_sub_f32_e32 v125, v125, v88
	v_exp_f32_e32 v118, v118
	v_exp_f32_e32 v119, v119
	v_exp_f32_e32 v120, v120
	v_exp_f32_e32 v121, v121
	v_exp_f32_e32 v122, v122
	v_exp_f32_e32 v123, v123
	v_exp_f32_e32 v124, v124
	v_exp_f32_e32 v125, v125
	v_pk_add_f32 v[188:189], v[188:189], v[118:119]
	v_pk_add_f32 v[188:189], v[188:189], v[120:121]
	v_pk_add_f32 v[188:189], v[188:189], v[122:123]
	v_pk_add_f32 v[188:189], v[188:189], v[124:125]
	v_cvt_pk_bf16_f32 v118, v118, v119
	v_cvt_pk_bf16_f32 v119, v120, v121
	v_cvt_pk_bf16_f32 v120, v122, v123
	v_cvt_pk_bf16_f32 v121, v124, v125
	s_nop 1
	s_waitcnt lgkmcnt(4)
	v_mfma_f32_32x32x16_bf16 v[18:33], v[34:37], v[118:121], v[18:33]
	v_mfma_f32_32x32x16_bf16 v[2:17], v[38:41], v[118:121], v[2:17]
	ds_read_b64 v[34:35], v190 offset:55680
	ds_read_b64 v[36:37], v191 offset:55680
	ds_read_b64 v[38:39], v194 offset:55680
	ds_read_b64 v[40:41], v195 offset:55680
	v_sub_f32_e32 v126, v126, v88
	v_sub_f32_e32 v127, v127, v88
	v_sub_f32_e32 v128, v128, v88
	v_sub_f32_e32 v129, v129, v88
	v_sub_f32_e32 v130, v130, v88
	v_sub_f32_e32 v131, v131, v88
	v_sub_f32_e32 v132, v132, v88
	v_sub_f32_e32 v133, v133, v88
	v_exp_f32_e32 v126, v126
	v_exp_f32_e32 v127, v127
	v_exp_f32_e32 v128, v128
	v_exp_f32_e32 v129, v129
	v_exp_f32_e32 v130, v130
	v_exp_f32_e32 v131, v131
	v_exp_f32_e32 v132, v132
	v_exp_f32_e32 v133, v133
	v_pk_add_f32 v[188:189], v[188:189], v[126:127]
	v_pk_add_f32 v[188:189], v[188:189], v[128:129]
	v_pk_add_f32 v[188:189], v[188:189], v[130:131]
	v_pk_add_f32 v[188:189], v[188:189], v[132:133]
	v_cvt_pk_bf16_f32 v126, v126, v127
	v_cvt_pk_bf16_f32 v127, v128, v129
	v_cvt_pk_bf16_f32 v128, v130, v131
	v_cvt_pk_bf16_f32 v129, v132, v133
	s_nop 1
	s_waitcnt lgkmcnt(4)
	v_mfma_f32_32x32x16_bf16 v[18:33], v[42:45], v[126:129], v[18:33]
	v_mfma_f32_32x32x16_bf16 v[2:17], v[46:49], v[126:129], v[2:17]
	ds_read_b64 v[42:43], v192 offset:55680
	ds_read_b64 v[44:45], v193 offset:55680
	ds_read_b64 v[46:47], v196 offset:55680
	ds_read_b64 v[48:49], v197 offset:55680
	v_sub_f32_e32 v134, v134, v88
	v_sub_f32_e32 v135, v135, v88
	v_sub_f32_e32 v136, v136, v88
	v_sub_f32_e32 v137, v137, v88
	v_sub_f32_e32 v138, v138, v88
	v_sub_f32_e32 v139, v139, v88
	v_sub_f32_e32 v140, v140, v88
	v_sub_f32_e32 v141, v141, v88
	v_exp_f32_e32 v134, v134
	v_exp_f32_e32 v135, v135
	v_exp_f32_e32 v136, v136
	v_exp_f32_e32 v137, v137
	v_exp_f32_e32 v138, v138
	v_exp_f32_e32 v139, v139
	v_exp_f32_e32 v140, v140
	v_exp_f32_e32 v141, v141
	v_pk_add_f32 v[188:189], v[188:189], v[134:135]
	v_pk_add_f32 v[188:189], v[188:189], v[136:137]
	v_pk_add_f32 v[188:189], v[188:189], v[138:139]
	v_pk_add_f32 v[188:189], v[188:189], v[140:141]
	v_cvt_pk_bf16_f32 v134, v134, v135
	v_cvt_pk_bf16_f32 v135, v136, v137
	v_cvt_pk_bf16_f32 v136, v138, v139
	v_cvt_pk_bf16_f32 v137, v140, v141
	s_nop 1
	s_waitcnt lgkmcnt(4)
	v_mfma_f32_32x32x16_bf16 v[18:33], v[34:37], v[134:137], v[18:33]
	v_mfma_f32_32x32x16_bf16 v[2:17], v[38:41], v[134:137], v[2:17]
	ds_read_b64 v[34:35], v190 offset:55744
	ds_read_b64 v[36:37], v191 offset:55744
	ds_read_b64 v[38:39], v194 offset:55744
	ds_read_b64 v[40:41], v195 offset:55744
	v_sub_f32_e32 v142, v142, v88
	v_sub_f32_e32 v143, v143, v88
	v_sub_f32_e32 v144, v144, v88
	v_sub_f32_e32 v145, v145, v88
	v_sub_f32_e32 v146, v146, v88
	v_sub_f32_e32 v147, v147, v88
	v_sub_f32_e32 v148, v148, v88
	v_sub_f32_e32 v149, v149, v88
	v_exp_f32_e32 v142, v142
	v_exp_f32_e32 v143, v143
	v_exp_f32_e32 v144, v144
	v_exp_f32_e32 v145, v145
	v_exp_f32_e32 v146, v146
	v_exp_f32_e32 v147, v147
	v_exp_f32_e32 v148, v148
	v_exp_f32_e32 v149, v149
	v_pk_add_f32 v[188:189], v[188:189], v[142:143]
	v_pk_add_f32 v[188:189], v[188:189], v[144:145]
	v_pk_add_f32 v[188:189], v[188:189], v[146:147]
	v_pk_add_f32 v[188:189], v[188:189], v[148:149]
	v_cvt_pk_bf16_f32 v142, v142, v143
	v_cvt_pk_bf16_f32 v143, v144, v145
	v_cvt_pk_bf16_f32 v144, v146, v147
	v_cvt_pk_bf16_f32 v145, v148, v149
	s_nop 1
	s_waitcnt lgkmcnt(4)
; #define LAS __attribute__((address_space(3)))
; DI float ex2(float x) { return __builtin_amdgcn_exp2f(x); }
; DI float lg2(float x) { return __builtin_amdgcn_logf(x); }
; #define MFMA32(a, b, c) __builtin_amdgcn_mfma_f32_32x32x16_bf16((a), (b), (c), 0, 0, 0)
; #define VFRAG2(off) __builtin_shufflevector(*(const LAS s16x4*)(vp + (((off) + 4 * hh) ^ sw)), *(const LAS s16x4*)(vp + (((off) + 8 + 4 * hh) ^ sw)), 0, 1, 2, 3, 4, 5, 6, 7)
; DI void attn_dil_unit(LAS unsigned char* lds, const AttnArgs a) {
;     ...
;     for (int j = 0; j < 5; ++j)
; #pragma unroll
;         for (int i = 0; i < 16; ++i) { const float p = (sc[j][i] > -1e29f) ? ex2(sc[j][i] - mx) : 0.f; sc[j][i] = p; ls += p; }
;     const float lt = ls + __shfl_xor(ls, 32);
;     f32x16 o[2];
; #pragma unroll
;     for (int d = 0; d < 2; ++d)
; #pragma unroll
;         for (int i = 0; i < 16; ++i) o[d][i] = 0.f;
; #pragma unroll
;     for (int j = 0; j < 5; ++j) {
;         const bf16x8 pb0 = pack8(sc[j], 0), pb1 = pack8(sc[j], 1);
; #pragma unroll
;         for (int d = 0; d < 2; ++d) {
;             const LAS bf16_t* vp = Vl + (d * 32 + r32) * VLD + 32 * wid + 32 * j;
;             const int sw = (((d * 32 + r32) >> 3) & 7) << 2;
;     ...
;             o[d] = MFMA32(VFRAG2(0), pb0, o[d]);
;             o[d] = MFMA32(VFRAG2(16), pb1, o[d]);
;     ...
;         }
;     }
;     const float inv = 1.0f / lt;
;     if (hh == 0) a.lse[qtok * a.ldl] = mx + lg2(lt);
	v_mfma_f32_32x32x16_bf16 v[18:33], v[42:45], v[142:145], v[18:33]
	v_mfma_f32_32x32x16_bf16 v[2:17], v[46:49], v[142:145], v[2:17]
	ds_read_b64 v[42:43], v192 offset:55744
	ds_read_b64 v[44:45], v193 offset:55744
	ds_read_b64 v[46:47], v196 offset:55744
	ds_read_b64 v[48:49], v197 offset:55744
	v_sub_f32_e32 v150, v150, v88
	v_sub_f32_e32 v151, v151, v88
	v_sub_f32_e32 v152, v152, v88
	v_sub_f32_e32 v153, v153, v88
	v_sub_f32_e32 v154, v154, v88
	v_sub_f32_e32 v155, v155, v88
	v_sub_f32_e32 v156, v156, v88
	v_sub_f32_e32 v157, v157, v88
	v_exp_f32_e32 v150, v150
	v_exp_f32_e32 v151, v151
	v_exp_f32_e32 v152, v152
	v_exp_f32_e32 v153, v153
	v_exp_f32_e32 v154, v154
	v_exp_f32_e32 v155, v155
	v_exp_f32_e32 v156, v156
	v_exp_f32_e32 v157, v157
	v_pk_add_f32 v[188:189], v[188:189], v[150:151]
	v_pk_add_f32 v[188:189], v[188:189], v[152:153]
	v_pk_add_f32 v[188:189], v[188:189], v[154:155]
	v_pk_add_f32 v[188:189], v[188:189], v[156:157]
	v_cvt_pk_bf16_f32 v150, v150, v151
	v_cvt_pk_bf16_f32 v151, v152, v153
	v_cvt_pk_bf16_f32 v152, v154, v155
	v_cvt_pk_bf16_f32 v153, v156, v157
	s_nop 1
	s_waitcnt lgkmcnt(4)
	v_mfma_f32_32x32x16_bf16 v[18:33], v[34:37], v[150:153], v[18:33]
	v_mfma_f32_32x32x16_bf16 v[2:17], v[38:41], v[150:153], v[2:17]
	ds_read_b64 v[34:35], v190 offset:55808
	ds_read_b64 v[36:37], v191 offset:55808
	ds_read_b64 v[38:39], v194 offset:55808
	ds_read_b64 v[40:41], v195 offset:55808
	v_sub_f32_e32 v158, v158, v88
	v_sub_f32_e32 v159, v159, v88
	v_sub_f32_e32 v160, v160, v88
	v_sub_f32_e32 v161, v161, v88
	v_sub_f32_e32 v162, v162, v88
	v_sub_f32_e32 v163, v163, v88
	v_sub_f32_e32 v164, v164, v88
	v_sub_f32_e32 v165, v165, v88
	v_exp_f32_e32 v158, v158
	v_exp_f32_e32 v159, v159
	v_exp_f32_e32 v160, v160
	v_exp_f32_e32 v161, v161
	v_exp_f32_e32 v162, v162
	v_exp_f32_e32 v163, v163
	v_exp_f32_e32 v164, v164
	v_exp_f32_e32 v165, v165
	v_pk_add_f32 v[188:189], v[188:189], v[158:159]
	v_pk_add_f32 v[188:189], v[188:189], v[160:161]
	v_pk_add_f32 v[188:189], v[188:189], v[162:163]
	v_pk_add_f32 v[188:189], v[188:189], v[164:165]
	v_cvt_pk_bf16_f32 v158, v158, v159
	v_cvt_pk_bf16_f32 v159, v160, v161
	v_cvt_pk_bf16_f32 v160, v162, v163
	v_cvt_pk_bf16_f32 v161, v164, v165
	s_nop 1
	s_waitcnt lgkmcnt(4)
	v_mfma_f32_32x32x16_bf16 v[18:33], v[42:45], v[158:161], v[18:33]
	v_mfma_f32_32x32x16_bf16 v[2:17], v[46:49], v[158:161], v[2:17]
	ds_read_b64 v[42:43], v192 offset:55808
	ds_read_b64 v[44:45], v193 offset:55808
	ds_read_b64 v[46:47], v196 offset:55808
	ds_read_b64 v[48:49], v197 offset:55808
	v_sub_f32_e32 v166, v166, v88
	v_sub_f32_e32 v167, v167, v88
	v_sub_f32_e32 v168, v168, v88
	v_sub_f32_e32 v169, v169, v88
	v_sub_f32_e32 v170, v170, v88
	v_sub_f32_e32 v171, v171, v88
	v_sub_f32_e32 v172, v172, v88
	v_sub_f32_e32 v173, v173, v88
	v_exp_f32_e32 v166, v166
	v_exp_f32_e32 v167, v167
	v_exp_f32_e32 v168, v168
	v_exp_f32_e32 v169, v169
	v_exp_f32_e32 v170, v170
	v_exp_f32_e32 v171, v171
	v_exp_f32_e32 v172, v172
	v_exp_f32_e32 v173, v173
	v_pk_add_f32 v[188:189], v[188:189], v[166:167]
	v_pk_add_f32 v[188:189], v[188:189], v[168:169]
	v_pk_add_f32 v[188:189], v[188:189], v[170:171]
	v_pk_add_f32 v[188:189], v[188:189], v[172:173]
	v_cvt_pk_bf16_f32 v166, v166, v167
	v_cvt_pk_bf16_f32 v167, v168, v169
	v_cvt_pk_bf16_f32 v168, v170, v171
	v_cvt_pk_bf16_f32 v169, v172, v173
	s_nop 1
	s_waitcnt lgkmcnt(4)
	v_mfma_f32_32x32x16_bf16 v[18:33], v[34:37], v[166:169], v[18:33]
	v_mfma_f32_32x32x16_bf16 v[2:17], v[38:41], v[166:169], v[2:17]
	v_sub_f32_e32 v174, v174, v88
	v_sub_f32_e32 v175, v175, v88
	v_sub_f32_e32 v176, v176, v88
	v_sub_f32_e32 v177, v177, v88
	v_sub_f32_e32 v178, v178, v88
	v_sub_f32_e32 v179, v179, v88
	v_sub_f32_e32 v180, v180, v88
	v_sub_f32_e32 v181, v181, v88
	v_exp_f32_e32 v174, v174
	v_exp_f32_e32 v175, v175
	v_exp_f32_e32 v176, v176
	v_exp_f32_e32 v177, v177
	v_exp_f32_e32 v178, v178
	v_exp_f32_e32 v179, v179
	v_exp_f32_e32 v180, v180
	v_exp_f32_e32 v181, v181
	v_pk_add_f32 v[188:189], v[188:189], v[174:175]
	v_pk_add_f32 v[188:189], v[188:189], v[176:177]
	v_pk_add_f32 v[188:189], v[188:189], v[178:179]
	v_pk_add_f32 v[188:189], v[188:189], v[180:181]
	v_cvt_pk_bf16_f32 v174, v174, v175
	v_cvt_pk_bf16_f32 v175, v176, v177
	v_cvt_pk_bf16_f32 v176, v178, v179
	v_cvt_pk_bf16_f32 v177, v180, v181
	s_nop 1
	s_waitcnt lgkmcnt(0)
	v_mfma_f32_32x32x16_bf16 v[18:33], v[42:45], v[174:177], v[18:33]
	v_mfma_f32_32x32x16_bf16 v[2:17], v[46:49], v[174:177], v[2:17]
	v_add_f32_e32 v188, v188, v189
	ds_bpermute_b32 v0, v199, v188
	v_lshlrev_b32_e32 v92, 2, v100
	v_cmp_eq_u32_e32 vcc, 0, v100
	s_waitcnt lgkmcnt(0)
	v_add_f32_e32 v0, v188, v0
	s_and_saveexec_b64 s[6:7], vcc
	s_cbranch_execz .LBB0_227
	s_lshl_b64 s[0:1], s[14:15], 18
	v_readlane_b32 s4, v255, 9
	v_log_f32_e32 v34, v0
	v_readlane_b32 s5, v255, 10
	s_add_u32 s0, s4, s0
	s_addc_u32 s1, s5, s1
	s_lshl_b32 s4, s21, 2
	s_add_u32 s0, s0, s4
	s_addc_u32 s1, s1, 0
	v_add_f32_e32 v36, v88, v34
	v_lshlrev_b64 v[34:35], 5, v[94:95]
	v_lshl_add_u64 v[34:35], s[0:1], 0, v[34:35]
	global_store_dword v[34:35], v36, off
	s_branch .LBB0_227

;     DI bool next(int i_, Unit& u) const {
;         const int i = (npass == 1) ? i_ : i_ / npass, b = i_ - i * npass;
;         const long L = (long)i * G + c; if (L >= nwg) return false;
;         int wgid = (int)L; { const int q = nwg / NXCD, r = nwg % NXCD, xcd = wgid % NXCD, off = wgid / NXCD; wgid = (xcd < r ? xcd * (q + 1) : r * (q + 1) + (xcd - r) * q) + off; }
;         const int nig = WGM * nN, gid = wgid / nig, fm = gid * WGM, gsz = (nM - fm) < WGM ? (nM - fm) : WGM;
;         u.pm = fm + ((wgid % nig) % gsz) + b * pms; u.pn = (wgid % nig) / gsz + b * pns; return true;
;     DI void operator()(const f32x4 (&acc)[2][2][4][2], const Unit& u, int wr, int wc, int fr, int fq) const {
;         const int row0 = u.pm * BM + wr * 64 + fr, col0 = u.pn * BM + wc * 32 + 8 * fq;
;         float ssv[2][4];
; #pragma unroll
;         for (int ai = 0; ai < 2; ++ai)
; #pragma unroll
;             for (int m = 0; m < 4; ++m) ssv[ai][m] = ss ? ss[row0 + ai * HALF + m * 16] : 0.f;
.LBB0_430:
	s_lshl_b32 s98, s1, 8
	s_add_i32 s98, s98, s59
	v_and_or_b32 v222, v202, 15, s98
	v_ashrrev_i32_e32 v223, 31, v222
	v_lshl_add_u64 v[222:223], v[222:223], 2, s[26:27]
	global_load_dword v224, v[222:223], off
	global_load_dword v225, v[222:223], off offset:64
	global_load_dword v226, v[222:223], off offset:128
	global_load_dword v227, v[222:223], off offset:192
	global_load_dword v228, v[222:223], off offset:512
	global_load_dword v229, v[222:223], off offset:576
	global_load_dword v230, v[222:223], off offset:640
	global_load_dword v231, v[222:223], off offset:704
	v_readlane_b32 s8, v255, 1
	s_add_i32 s63, s63, 1
	v_readlane_b32 s9, v255, 2
	s_mul_i32 s4, s63, s9
	s_mul_hi_u32 s5, s63, s8
	s_add_i32 s5, s5, s4
	s_mul_i32 s4, s63, s8
	s_add_u32 s12, s4, s76
	s_addc_u32 s13, s5, s77
	v_mov_b64_e32 v[2:3], 0x4e0
	v_cmp_lt_i64_e64 s[8:9], s[12:13], v[2:3]
	v_mov_b64_e32 v[2:3], 0x4df
	v_cmp_gt_i64_e32 vcc, s[12:13], v[2:3]
	s_cbranch_vccnz .LBB0_432
	s_ashr_i32 s4, s12, 31
	s_lshr_b32 s4, s4, 29
	s_add_i32 s4, s12, s4
	s_ashr_i32 s5, s4, 3
	s_and_b32 s4, s4, -8
	s_sub_i32 s4, s12, s4
	s_cmp_lt_i32 s4, 0
	s_movk_i32 s12, 0x9d
	s_cselect_b32 s12, s12, 0x9c
	s_mul_i32 s4, s4, s12
	s_add_i32 s4, s4, s5
	s_mul_hi_i32 s5, s4, 0xd20d20d3
	s_add_i32 s5, s5, s4
	s_lshr_b32 s12, s5, 31
	s_ashr_i32 s5, s5, 8
	s_add_i32 s5, s5, s12
	s_lshl_b32 s12, s5, 3
	s_sub_i32 s13, 32, s12
	s_min_i32 s13, s13, 8
	s_abs_i32 s14, s13
	v_cvt_f32_u32_e32 v2, s14
	s_sub_i32 s16, 0, s14
	s_mulk_i32 s5, 0x138
	s_sub_i32 s4, s4, s5
	v_rcp_iflag_f32_e32 v2, v2
	s_abs_i32 s5, s4
	s_xor_b32 s15, s4, s13
	s_ashr_i32 s15, s15, 31
	v_mul_f32_e32 v2, 0x4f7ffffe, v2
	v_cvt_u32_f32_e32 v2, v2
	s_nop 0
	v_readfirstlane_b32 s17, v2
	s_mul_i32 s16, s16, s17
	s_mul_hi_u32 s16, s17, s16
	s_add_i32 s17, s17, s16
	s_mul_hi_u32 s16, s5, s17
	s_mul_i32 s17, s16, s14
	s_sub_i32 s5, s5, s17
	s_add_i32 s33, s16, 1
	s_sub_i32 s17, s5, s14
	s_cmp_ge_u32 s5, s14
	s_cselect_b32 s16, s33, s16
	s_cselect_b32 s5, s17, s5
	s_add_i32 s17, s16, 1
	s_cmp_ge_u32 s5, s14
	s_cselect_b32 s5, s17, s16
	s_xor_b32 s5, s5, s15
	s_sub_i32 s40, s5, s15
	s_mul_i32 s5, s40, s13
	s_sub_i32 s4, s4, s5
	s_add_i32 s42, s12, s4

;     DI void operator()(const f32x4 (&acc)[2][2][4][2], const Unit& u, int wr, int wc, int fr, int fq) const {
;         const int row0 = u.pm * BM + wr * 64 + fr, col0 = u.pn * BM + wc * 32 + 8 * fq;
;         float ssv[2][4];
; #pragma unroll
;         for (int ai = 0; ai < 2; ++ai)
; #pragma unroll
;             for (int m = 0; m < 4; ++m) ssv[ai][m] = ss ? ss[row0 + ai * HALF + m * 16] : 0.f;
; #pragma unroll
;         for (int ai = 0; ai < 2; ++ai)
; #pragma unroll
;             for (int m = 0; m < 4; ++m) {
;                 const int r = row0 + ai * HALF + m * 16;
;                 const float rs = ss ? __builtin_amdgcn_rsqf(ssv[ai][m] * inv_dim + EPS) : 1.f;
.LBB0_436:
	s_lshl_b32 s1, s1, 8
	v_mov_b32_e32 v144, v202
	s_add_i32 s1, s1, s59
	v_cndmask_b32_e64 v141, 0, 1, s[30:31]
	v_and_or_b32 v140, v144, 15, s1
	v_mov_b32_e32 v157, 0x358637bd
	v_cmp_ne_u32_e64 s[6:7], 1, v141
	s_andn2_b64 vcc, exec, s[30:31]
	v_ashrrev_i32_e32 v141, 31, v140
	v_mov_b32_e32 v145, 0x358637bd
	s_cbranch_vccnz .LBB0_531
	v_fmamk_f32 v145, v224, 0x3a800000, v252
	v_fmamk_f32 v157, v225, 0x3a800000, v252
	v_fmamk_f32 v156, v226, 0x3a800000, v252
	v_fmamk_f32 v155, v227, 0x3a800000, v252
	v_fmamk_f32 v154, v228, 0x3a800000, v252
	v_fmamk_f32 v153, v229, 0x3a800000, v252
	v_fmamk_f32 v152, v230, 0x3a800000, v252
	v_fmamk_f32 v150, v231, 0x3a800000, v252
	s_branch .LBB0_448
